# indexer static work table re-balanced (items of workgroups 0-63 traded with 192-255 so the g2-carrying workgroups get fewer tiles); on top of GEMM setprio flips removed
# baseline (speedup 1.0000x reference)
; #define PG8_STAGE(bufoff, gbase, voff) do { _Pragma("unroll") for (int _i = 0; _i < 2; ++_i) \
;         __builtin_amdgcn_global_load_lds((const unsigned*)((const char*)(gbase) + (voff)[_i]), (PG8_LAS unsigned*)(lds + (bufoff) + ldsw + _i * 8192), 16, 0, 0); } while (0)
; #define PG8_LDA(dst, b, h) do { _Pragma("unroll") for (int m = 0; m < 4; ++m) _Pragma("unroll") for (int k = 0; k < 2; ++k) dst[m][k] = *(const PG8_LAS bf16x8*)(lds + PG8_SA(b, h) + aoff + m * 2048 + k * 1024); } while (0)
; #define PG8_LDB(dst, b, h) do { _Pragma("unroll") for (int n = 0; n < 2; ++n) _Pragma("unroll") for (int k = 0; k < 2; ++k) dst[n][k] = *(const PG8_LAS bf16x8*)(lds + PG8_SB(b, h) + boff + n * 2048 + k * 1024); } while (0)
; #define PG8_MMA(ai, bj, At, Bt) do { __builtin_amdgcn_s_setprio(1); _Pragma("unroll") for (int m = 0; m < 4; ++m) _Pragma("unroll") for (int n = 0; n < 2; ++n) _Pragma("unroll") for (int k = 0; k < 2; ++k) \
;         acc[ai][bj][m][n] = __builtin_amdgcn_mfma_f32_16x16x32_bf16(Bt[n][k], At[m][k], acc[ai][bj][m][n], 0, 0, 0); __builtin_amdgcn_s_setprio(0); } while (0)
; #define PG8_WAIT_V(n) asm volatile("s_waitcnt vmcnt(" #n ")" ::: "memory")
; #define PG8_WAIT_L(n) asm volatile("s_waitcnt lgkmcnt(" #n ")" ::: "memory")
; #define PG8_BAR __builtin_amdgcn_s_barrier()
; #define PG8_SCHED __builtin_amdgcn_sched_barrier(0)
; template <class Epi, class Sched, bool ALIGN_EPI = false, bool SP2 = false>
; __device__ __forceinline__ void gemm_phase(PG8_LAS unsigned char* lds, const Gemm g, const Sched& S, const Epi& E) {
;     ...
;             PG8_LDB(B0, 0, 0); PG8_LDB(B1, 0, 1); PG8_SCHED; PG8_LDA(At, 0, 0); PG8_STAGE(PG8_SA(1, 1), a1 + hstepA, voffA);
;             PG8_WAIT_V(8); PG8_WAIT_L(0); PG8_BAR; PG8_MMA(0, 0, At, B0); PG8_MMA(0, 1, At, B1); PG8_BAR; PG8_SCHED;
;             PG8_LDA(At, 0, 1); PG8_STAGE(PG8_SB(0, 0), b2, voffB); PG8_STAGE(PG8_SB(0, 1), b2 + hstepB, voffB); PG8_STAGE(PG8_SA(0, 0), a2, voffA);
;             PG8_WAIT_V(8); PG8_WAIT_L(0); PG8_BAR; PG8_MMA(1, 0, At, B0); PG8_MMA(1, 1, At, B1); PG8_BAR; PG8_SCHED;
;             PG8_LDB(B0, 1, 0); PG8_LDB(B1, 1, 1); PG8_SCHED; PG8_LDA(At, 1, 0); PG8_STAGE(PG8_SA(0, 1), a2 + hstepA, voffA);
.LBB0_228:
	ds_read_b128 v[148:151], v153
	ds_read_b128 v[156:159], v153 offset:1024
	ds_read_b128 v[160:163], v153 offset:2048
	ds_read_b128 v[164:167], v153 offset:3072
	ds_read_b128 v[168:171], v154
	ds_read_b128 v[172:175], v154 offset:1024
	ds_read_b128 v[176:179], v154 offset:2048
	ds_read_b128 v[180:183], v154 offset:3072
	s_add_u32 s22, s20, 0xfff80080
	s_addc_u32 s23, s21, -1
	s_cmp_eq_u32 s53, 28
	s_cselect_b32 s25, s13, s23
	s_cselect_b32 s24, s49, s22
	s_cselect_b32 s23, s11, s52
	s_cselect_b32 s22, s50, s51
	v_lshl_add_u64 v[216:217], s[20:21], 0, v[140:141]
	s_add_i32 m0, s19, 0xc000
	ds_read_b128 v[184:187], v155
	ds_read_b128 v[188:191], v155 offset:1024
	ds_read_b128 v[192:195], v155 offset:2048
	ds_read_b128 v[196:199], v155 offset:3072
	ds_read_b128 v[200:203], v155 offset:4096
	ds_read_b128 v[204:207], v155 offset:5120
	ds_read_b128 v[208:211], v155 offset:6144
	ds_read_b128 v[212:215], v155 offset:7168
	global_load_lds_dwordx4 v[216:217], off
	v_lshl_add_u64 v[216:217], s[20:21], 0, v[142:143]
	s_add_i32 m0, s19, 0xe000
	s_nop 0
	global_load_lds_dwordx4 v[216:217], off
	s_waitcnt vmcnt(8)
	s_waitcnt lgkmcnt(0)
	s_barrier
	s_waitcnt lgkmcnt(0)
	v_mfma_f32_16x16x32_bf16 v[124:127], v[148:151], v[184:187], v[124:127]
	v_mfma_f32_16x16x32_bf16 v[120:123], v[160:163], v[184:187], v[120:123]
	v_mfma_f32_16x16x32_bf16 v[116:119], v[148:151], v[192:195], v[116:119]
	v_mfma_f32_16x16x32_bf16 v[108:111], v[160:163], v[192:195], v[108:111]
	v_mfma_f32_16x16x32_bf16 v[100:103], v[148:151], v[200:203], v[100:103]
	v_mfma_f32_16x16x32_bf16 v[92:95], v[160:163], v[200:203], v[92:95]
	v_mfma_f32_16x16x32_bf16 v[84:87], v[148:151], v[208:211], v[84:87]
	v_mfma_f32_16x16x32_bf16 v[76:79], v[160:163], v[208:211], v[76:79]
	v_mfma_f32_16x16x32_bf16 v[124:127], v[156:159], v[188:191], v[124:127]
	v_mfma_f32_16x16x32_bf16 v[120:123], v[164:167], v[188:191], v[120:123]
	v_mfma_f32_16x16x32_bf16 v[116:119], v[156:159], v[196:199], v[116:119]
	v_mfma_f32_16x16x32_bf16 v[108:111], v[164:167], v[196:199], v[108:111]
	v_mfma_f32_16x16x32_bf16 v[100:103], v[156:159], v[204:207], v[100:103]
	v_mfma_f32_16x16x32_bf16 v[92:95], v[164:167], v[204:207], v[92:95]
	v_mfma_f32_16x16x32_bf16 v[84:87], v[156:159], v[212:215], v[84:87]
	v_mfma_f32_16x16x32_bf16 v[76:79], v[164:167], v[212:215], v[76:79]
	v_mfma_f32_16x16x32_bf16 v[112:115], v[168:171], v[184:187], v[112:115]
	v_mfma_f32_16x16x32_bf16 v[104:107], v[176:179], v[184:187], v[104:107]
	v_mfma_f32_16x16x32_bf16 v[96:99], v[168:171], v[192:195], v[96:99]
	v_mfma_f32_16x16x32_bf16 v[88:91], v[176:179], v[192:195], v[88:91]
	v_mfma_f32_16x16x32_bf16 v[80:83], v[168:171], v[200:203], v[80:83]
	v_mfma_f32_16x16x32_bf16 v[72:75], v[176:179], v[200:203], v[72:75]
	v_mfma_f32_16x16x32_bf16 v[68:71], v[168:171], v[208:211], v[68:71]
	v_mfma_f32_16x16x32_bf16 v[64:67], v[176:179], v[208:211], v[64:67]
	v_mfma_f32_16x16x32_bf16 v[112:115], v[172:175], v[188:191], v[112:115]
	v_mfma_f32_16x16x32_bf16 v[104:107], v[180:183], v[188:191], v[104:107]
	v_mfma_f32_16x16x32_bf16 v[96:99], v[172:175], v[196:199], v[96:99]
	v_mfma_f32_16x16x32_bf16 v[88:91], v[180:183], v[196:199], v[88:91]
	v_mfma_f32_16x16x32_bf16 v[80:83], v[172:175], v[204:207], v[80:83]
	v_mfma_f32_16x16x32_bf16 v[72:75], v[180:183], v[204:207], v[72:75]
	v_mfma_f32_16x16x32_bf16 v[68:71], v[172:175], v[212:215], v[68:71]
	v_mfma_f32_16x16x32_bf16 v[64:67], v[180:183], v[212:215], v[64:67]
	s_barrier
	s_add_i32 s54, s41, s31
	v_lshl_add_u64 v[216:217], s[22:23], 0, v[134:135]
	s_mov_b32 m0, s54
	ds_read_b128 v[184:187], v155 offset:16384
	ds_read_b128 v[188:191], v155 offset:17408
	ds_read_b128 v[192:195], v155 offset:18432
	ds_read_b128 v[196:199], v155 offset:19456
	ds_read_b128 v[200:203], v155 offset:20480
	ds_read_b128 v[204:207], v155 offset:21504
	ds_read_b128 v[208:211], v155 offset:22528
	ds_read_b128 v[212:215], v155 offset:23552
	global_load_lds_dwordx4 v[216:217], off
	s_add_i32 m0, s54, 0x2000
	s_add_u32 s54, s22, 0x80000
	v_lshl_add_u64 v[218:219], s[22:23], 0, v[138:139]
	s_addc_u32 s55, s23, 0
	s_add_i32 s56, s42, s31
	global_load_lds_dwordx4 v[218:219], off
	v_lshl_add_u64 v[220:221], s[54:55], 0, v[134:135]
	s_mov_b32 m0, s56
	v_lshl_add_u64 v[222:223], s[24:25], 0, v[136:137]
	global_load_lds_dwordx4 v[220:221], off
	v_lshl_add_u64 v[220:221], s[54:55], 0, v[138:139]
	s_add_i32 m0, s56, 0x2000
	s_nop 0
	global_load_lds_dwordx4 v[220:221], off
	v_lshl_add_u64 v[220:221], s[24:25], 0, v[132:133]
	s_mov_b32 m0, s19
	s_nop 0
	global_load_lds_dwordx4 v[220:221], off
	s_mov_b32 m0, s33
	s_nop 0
	global_load_lds_dwordx4 v[222:223], off
	s_waitcnt vmcnt(8)
	s_waitcnt lgkmcnt(0)
	s_barrier
; #define PG8_STAGE(bufoff, gbase, voff) do { _Pragma("unroll") for (int _i = 0; _i < 2; ++_i) \
;         __builtin_amdgcn_global_load_lds((const unsigned*)((const char*)(gbase) + (voff)[_i]), (PG8_LAS unsigned*)(lds + (bufoff) + ldsw + _i * 8192), 16, 0, 0); } while (0)
; #define PG8_LDA(dst, b, h) do { _Pragma("unroll") for (int m = 0; m < 4; ++m) _Pragma("unroll") for (int k = 0; k < 2; ++k) dst[m][k] = *(const PG8_LAS bf16x8*)(lds + PG8_SA(b, h) + aoff + m * 2048 + k * 1024); } while (0)
; #define PG8_LDB(dst, b, h) do { _Pragma("unroll") for (int n = 0; n < 2; ++n) _Pragma("unroll") for (int k = 0; k < 2; ++k) dst[n][k] = *(const PG8_LAS bf16x8*)(lds + PG8_SB(b, h) + boff + n * 2048 + k * 1024); } while (0)
; #define PG8_MMA(ai, bj, At, Bt) do { __builtin_amdgcn_s_setprio(1); _Pragma("unroll") for (int m = 0; m < 4; ++m) _Pragma("unroll") for (int n = 0; n < 2; ++n) _Pragma("unroll") for (int k = 0; k < 2; ++k) \
;         acc[ai][bj][m][n] = __builtin_amdgcn_mfma_f32_16x16x32_bf16(Bt[n][k], At[m][k], acc[ai][bj][m][n], 0, 0, 0); __builtin_amdgcn_s_setprio(0); } while (0)
; #define PG8_WAIT_V(n) asm volatile("s_waitcnt vmcnt(" #n ")" ::: "memory")
; #define PG8_WAIT_L(n) asm volatile("s_waitcnt lgkmcnt(" #n ")" ::: "memory")
; #define PG8_BAR __builtin_amdgcn_s_barrier()
; #define PG8_SCHED __builtin_amdgcn_sched_barrier(0)
; template <class Epi, class Sched, bool ALIGN_EPI = false, bool SP2 = false>
; __device__ __forceinline__ void gemm_phase(PG8_LAS unsigned char* lds, const Gemm g, const Sched& S, const Epi& E) {
;     ...
;             PG8_WAIT_V(8); PG8_WAIT_L(0); PG8_BAR; PG8_MMA(0, 0, At, B0); PG8_MMA(0, 1, At, B1); PG8_BAR; PG8_SCHED;
;             PG8_LDA(At, 0, 1); PG8_STAGE(PG8_SB(0, 0), b2, voffB); PG8_STAGE(PG8_SB(0, 1), b2 + hstepB, voffB); PG8_STAGE(PG8_SA(0, 0), a2, voffA);
;             PG8_WAIT_V(8); PG8_WAIT_L(0); PG8_BAR; PG8_MMA(1, 0, At, B0); PG8_MMA(1, 1, At, B1); PG8_BAR; PG8_SCHED;
;             PG8_LDB(B0, 1, 0); PG8_LDB(B1, 1, 1); PG8_SCHED; PG8_LDA(At, 1, 0); PG8_STAGE(PG8_SA(0, 1), a2 + hstepA, voffA);
;             PG8_WAIT_V(8); PG8_WAIT_L(0); PG8_BAR; PG8_MMA(0, 0, At, B0); PG8_MMA(0, 1, At, B1); PG8_BAR; PG8_SCHED;
;             PG8_LDA(At, 1, 1); PG8_STAGE(PG8_SB(1, 0), b3, voffB); PG8_STAGE(PG8_SB(1, 1), b3 + hstepB, voffB); PG8_STAGE(PG8_SA(1, 0), a3, voffA);
	s_waitcnt lgkmcnt(0)
	v_mfma_f32_16x16x32_bf16 v[60:63], v[148:151], v[184:187], v[60:63]
	v_mfma_f32_16x16x32_bf16 v[56:59], v[160:163], v[184:187], v[56:59]
	v_mfma_f32_16x16x32_bf16 v[52:55], v[148:151], v[192:195], v[52:55]
	v_mfma_f32_16x16x32_bf16 v[44:47], v[160:163], v[192:195], v[44:47]
	v_mfma_f32_16x16x32_bf16 v[36:39], v[148:151], v[200:203], v[36:39]
	v_mfma_f32_16x16x32_bf16 v[28:31], v[160:163], v[200:203], v[28:31]
	v_mfma_f32_16x16x32_bf16 v[20:23], v[148:151], v[208:211], v[20:23]
	v_mfma_f32_16x16x32_bf16 v[12:15], v[160:163], v[208:211], v[12:15]
	v_mfma_f32_16x16x32_bf16 v[60:63], v[156:159], v[188:191], v[60:63]
	v_mfma_f32_16x16x32_bf16 v[56:59], v[164:167], v[188:191], v[56:59]
	v_mfma_f32_16x16x32_bf16 v[52:55], v[156:159], v[196:199], v[52:55]
	v_mfma_f32_16x16x32_bf16 v[44:47], v[164:167], v[196:199], v[44:47]
	v_mfma_f32_16x16x32_bf16 v[36:39], v[156:159], v[204:207], v[36:39]
	v_mfma_f32_16x16x32_bf16 v[28:31], v[164:167], v[204:207], v[28:31]
	v_mfma_f32_16x16x32_bf16 v[20:23], v[156:159], v[212:215], v[20:23]
	v_mfma_f32_16x16x32_bf16 v[12:15], v[164:167], v[212:215], v[12:15]
	v_mfma_f32_16x16x32_bf16 v[48:51], v[168:171], v[184:187], v[48:51]
	v_mfma_f32_16x16x32_bf16 v[40:43], v[176:179], v[184:187], v[40:43]
	v_mfma_f32_16x16x32_bf16 v[32:35], v[168:171], v[192:195], v[32:35]
	v_mfma_f32_16x16x32_bf16 v[24:27], v[176:179], v[192:195], v[24:27]
	v_mfma_f32_16x16x32_bf16 v[16:19], v[168:171], v[200:203], v[16:19]
	v_mfma_f32_16x16x32_bf16 v[8:11], v[176:179], v[200:203], v[8:11]
	v_mfma_f32_16x16x32_bf16 v[4:7], v[168:171], v[208:211], v[4:7]
	v_mfma_f32_16x16x32_bf16 v[0:3], v[176:179], v[208:211], v[0:3]
	v_mfma_f32_16x16x32_bf16 v[48:51], v[172:175], v[188:191], v[48:51]
	v_mfma_f32_16x16x32_bf16 v[40:43], v[180:183], v[188:191], v[40:43]
	v_mfma_f32_16x16x32_bf16 v[32:35], v[172:175], v[196:199], v[32:35]
	v_mfma_f32_16x16x32_bf16 v[24:27], v[180:183], v[196:199], v[24:27]
	v_mfma_f32_16x16x32_bf16 v[16:19], v[172:175], v[204:207], v[16:19]
	v_mfma_f32_16x16x32_bf16 v[8:11], v[180:183], v[204:207], v[8:11]
	v_mfma_f32_16x16x32_bf16 v[4:7], v[172:175], v[212:215], v[4:7]
	v_mfma_f32_16x16x32_bf16 v[0:3], v[180:183], v[212:215], v[0:3]
	s_barrier
	s_add_i32 s54, 0, 0x18000
	s_add_i32 s55, 0, 0x1c000
	v_add_u32_e32 v164, s54, v131
	v_add_u32_e32 v180, s55, v131
	ds_read_b128 v[148:151], v164
	ds_read_b128 v[156:159], v164 offset:1024
	ds_read_b128 v[160:163], v164 offset:2048
	ds_read_b128 v[164:167], v164 offset:3072
	ds_read_b128 v[168:171], v180
	ds_read_b128 v[172:175], v180 offset:1024
	ds_read_b128 v[176:179], v180 offset:2048
	ds_read_b128 v[180:183], v180 offset:3072
	s_add_u32 s24, s24, 0x80000
	s_addc_u32 s25, s25, 0
	s_mov_b32 m0, s34
	v_lshl_add_u64 v[224:225], s[24:25], 0, v[132:133]
	ds_read_b128 v[184:187], v155 offset:32768
	ds_read_b128 v[188:191], v155 offset:33792
	ds_read_b128 v[192:195], v155 offset:34816
	ds_read_b128 v[196:199], v155 offset:35840
	ds_read_b128 v[200:203], v155 offset:36864
	ds_read_b128 v[204:207], v155 offset:37888
	ds_read_b128 v[208:211], v155 offset:38912
	ds_read_b128 v[212:215], v155 offset:39936
	global_load_lds_dwordx4 v[224:225], off
	v_lshl_add_u64 v[224:225], s[24:25], 0, v[136:137]
	s_mov_b32 m0, s35
	s_nop 0
	global_load_lds_dwordx4 v[224:225], off
	s_waitcnt vmcnt(8)
	s_waitcnt lgkmcnt(0)
	s_barrier
	s_waitcnt lgkmcnt(0)
	v_mfma_f32_16x16x32_bf16 v[124:127], v[148:151], v[184:187], v[124:127]
	v_mfma_f32_16x16x32_bf16 v[120:123], v[160:163], v[184:187], v[120:123]
	v_mfma_f32_16x16x32_bf16 v[116:119], v[148:151], v[192:195], v[116:119]
	v_mfma_f32_16x16x32_bf16 v[108:111], v[160:163], v[192:195], v[108:111]
	v_mfma_f32_16x16x32_bf16 v[100:103], v[148:151], v[200:203], v[100:103]
	v_mfma_f32_16x16x32_bf16 v[92:95], v[160:163], v[200:203], v[92:95]
	v_mfma_f32_16x16x32_bf16 v[84:87], v[148:151], v[208:211], v[84:87]
	v_mfma_f32_16x16x32_bf16 v[76:79], v[160:163], v[208:211], v[76:79]
	v_mfma_f32_16x16x32_bf16 v[124:127], v[156:159], v[188:191], v[124:127]
	v_mfma_f32_16x16x32_bf16 v[120:123], v[164:167], v[188:191], v[120:123]
	v_mfma_f32_16x16x32_bf16 v[116:119], v[156:159], v[196:199], v[116:119]
	v_mfma_f32_16x16x32_bf16 v[108:111], v[164:167], v[196:199], v[108:111]
	v_mfma_f32_16x16x32_bf16 v[100:103], v[156:159], v[204:207], v[100:103]
	v_mfma_f32_16x16x32_bf16 v[92:95], v[164:167], v[204:207], v[92:95]
	v_mfma_f32_16x16x32_bf16 v[84:87], v[156:159], v[212:215], v[84:87]
	v_mfma_f32_16x16x32_bf16 v[76:79], v[164:167], v[212:215], v[76:79]
	v_mfma_f32_16x16x32_bf16 v[112:115], v[168:171], v[184:187], v[112:115]
	v_mfma_f32_16x16x32_bf16 v[104:107], v[176:179], v[184:187], v[104:107]
	v_mfma_f32_16x16x32_bf16 v[96:99], v[168:171], v[192:195], v[96:99]
	v_mfma_f32_16x16x32_bf16 v[88:91], v[176:179], v[192:195], v[88:91]
	v_mfma_f32_16x16x32_bf16 v[80:83], v[168:171], v[200:203], v[80:83]
	v_mfma_f32_16x16x32_bf16 v[72:75], v[176:179], v[200:203], v[72:75]
	v_mfma_f32_16x16x32_bf16 v[68:71], v[168:171], v[208:211], v[68:71]
	v_mfma_f32_16x16x32_bf16 v[64:67], v[176:179], v[208:211], v[64:67]
	v_mfma_f32_16x16x32_bf16 v[112:115], v[172:175], v[188:191], v[112:115]
	v_mfma_f32_16x16x32_bf16 v[104:107], v[180:183], v[188:191], v[104:107]
	v_mfma_f32_16x16x32_bf16 v[96:99], v[172:175], v[196:199], v[96:99]
	v_mfma_f32_16x16x32_bf16 v[88:91], v[180:183], v[196:199], v[88:91]
	v_mfma_f32_16x16x32_bf16 v[80:83], v[172:175], v[204:207], v[80:83]
	v_mfma_f32_16x16x32_bf16 v[72:75], v[180:183], v[204:207], v[72:75]
	v_mfma_f32_16x16x32_bf16 v[68:71], v[172:175], v[212:215], v[68:71]
	v_mfma_f32_16x16x32_bf16 v[64:67], v[180:183], v[212:215], v[64:67]
	s_barrier
; #define PG8_STAGE(bufoff, gbase, voff) do { _Pragma("unroll") for (int _i = 0; _i < 2; ++_i) \
;         __builtin_amdgcn_global_load_lds((const unsigned*)((const char*)(gbase) + (voff)[_i]), (PG8_LAS unsigned*)(lds + (bufoff) + ldsw + _i * 8192), 16, 0, 0); } while (0)
; #define PG8_LDA(dst, b, h) do { _Pragma("unroll") for (int m = 0; m < 4; ++m) _Pragma("unroll") for (int k = 0; k < 2; ++k) dst[m][k] = *(const PG8_LAS bf16x8*)(lds + PG8_SA(b, h) + aoff + m * 2048 + k * 1024); } while (0)
; #define PG8_LDB(dst, b, h) do { _Pragma("unroll") for (int n = 0; n < 2; ++n) _Pragma("unroll") for (int k = 0; k < 2; ++k) dst[n][k] = *(const PG8_LAS bf16x8*)(lds + PG8_SB(b, h) + boff + n * 2048 + k * 1024); } while (0)
; #define PG8_MMA(ai, bj, At, Bt) do { __builtin_amdgcn_s_setprio(1); _Pragma("unroll") for (int m = 0; m < 4; ++m) _Pragma("unroll") for (int n = 0; n < 2; ++n) _Pragma("unroll") for (int k = 0; k < 2; ++k) \
;         acc[ai][bj][m][n] = __builtin_amdgcn_mfma_f32_16x16x32_bf16(Bt[n][k], At[m][k], acc[ai][bj][m][n], 0, 0, 0); __builtin_amdgcn_s_setprio(0); } while (0)
; #define PG8_WAIT_V(n) asm volatile("s_waitcnt vmcnt(" #n ")" ::: "memory")
; #define PG8_WAIT_L(n) asm volatile("s_waitcnt lgkmcnt(" #n ")" ::: "memory")
; #define PG8_BAR __builtin_amdgcn_s_barrier()
; #define PG8_SCHED __builtin_amdgcn_sched_barrier(0)
; template <class Epi, class Sched, bool ALIGN_EPI = false, bool SP2 = false>
; __device__ __forceinline__ void gemm_phase(PG8_LAS unsigned char* lds, const Gemm g, const Sched& S, const Epi& E) {
;     ...
;             PG8_LDB(B0, 1, 0); PG8_LDB(B1, 1, 1); PG8_SCHED; PG8_LDA(At, 1, 0); PG8_STAGE(PG8_SA(0, 1), a2 + hstepA, voffA);
;             PG8_WAIT_V(8); PG8_WAIT_L(0); PG8_BAR; PG8_MMA(0, 0, At, B0); PG8_MMA(0, 1, At, B1); PG8_BAR; PG8_SCHED;
;             PG8_LDA(At, 1, 1); PG8_STAGE(PG8_SB(1, 0), b3, voffB); PG8_STAGE(PG8_SB(1, 1), b3 + hstepB, voffB); PG8_STAGE(PG8_SA(1, 0), a3, voffA);
;             PG8_WAIT_V(8); PG8_WAIT_L(0); PG8_BAR; PG8_MMA(1, 0, At, B0); PG8_MMA(1, 1, At, B1); PG8_BAR; PG8_SCHED;
	s_add_i32 s24, s54, s31
	v_lshl_add_u64 v[216:217], v[216:217], 0, s[6:7]
	s_mov_b32 m0, s24
	ds_read_b128 v[184:187], v155 offset:49152
	ds_read_b128 v[188:191], v155 offset:50176
	ds_read_b128 v[192:195], v155 offset:51200
	ds_read_b128 v[196:199], v155 offset:52224
	ds_read_b128 v[200:203], v155 offset:53248
	ds_read_b128 v[204:207], v155 offset:54272
	ds_read_b128 v[208:211], v155 offset:55296
	ds_read_b128 v[212:215], v155 offset:56320
	global_load_lds_dwordx4 v[216:217], off
	s_add_i32 m0, s24, 0x2000
	s_add_u32 s22, s22, 0x80080
	v_lshl_add_u64 v[216:217], v[218:219], 0, s[6:7]
	s_addc_u32 s23, s23, 0
	s_add_i32 s24, s55, s31
	global_load_lds_dwordx4 v[216:217], off
	v_lshl_add_u64 v[216:217], s[22:23], 0, v[134:135]
	s_mov_b32 m0, s24
	s_nop 0
	global_load_lds_dwordx4 v[216:217], off
	v_lshl_add_u64 v[216:217], s[22:23], 0, v[138:139]
	s_add_i32 m0, s24, 0x2000
	s_nop 0
	global_load_lds_dwordx4 v[216:217], off
	v_lshl_add_u64 v[216:217], v[220:221], 0, s[6:7]
	s_mov_b32 m0, s37
	s_nop 0
	global_load_lds_dwordx4 v[216:217], off
	v_lshl_add_u64 v[216:217], v[222:223], 0, s[6:7]
	s_mov_b32 m0, s38
	s_nop 0
	global_load_lds_dwordx4 v[216:217], off
	s_waitcnt vmcnt(8)
	s_waitcnt lgkmcnt(0)
	s_barrier
	s_waitcnt lgkmcnt(0)
	v_mfma_f32_16x16x32_bf16 v[60:63], v[148:151], v[184:187], v[60:63]
	v_mfma_f32_16x16x32_bf16 v[56:59], v[160:163], v[184:187], v[56:59]
	v_mfma_f32_16x16x32_bf16 v[52:55], v[148:151], v[192:195], v[52:55]
	v_mfma_f32_16x16x32_bf16 v[44:47], v[160:163], v[192:195], v[44:47]
	v_mfma_f32_16x16x32_bf16 v[36:39], v[148:151], v[200:203], v[36:39]
	v_mfma_f32_16x16x32_bf16 v[28:31], v[160:163], v[200:203], v[28:31]
	v_mfma_f32_16x16x32_bf16 v[20:23], v[148:151], v[208:211], v[20:23]
	v_mfma_f32_16x16x32_bf16 v[12:15], v[160:163], v[208:211], v[12:15]
	v_mfma_f32_16x16x32_bf16 v[60:63], v[156:159], v[188:191], v[60:63]
	v_mfma_f32_16x16x32_bf16 v[56:59], v[164:167], v[188:191], v[56:59]
	v_mfma_f32_16x16x32_bf16 v[52:55], v[156:159], v[196:199], v[52:55]
	v_mfma_f32_16x16x32_bf16 v[44:47], v[164:167], v[196:199], v[44:47]
	v_mfma_f32_16x16x32_bf16 v[36:39], v[156:159], v[204:207], v[36:39]
	v_mfma_f32_16x16x32_bf16 v[28:31], v[164:167], v[204:207], v[28:31]
	v_mfma_f32_16x16x32_bf16 v[20:23], v[156:159], v[212:215], v[20:23]
	v_mfma_f32_16x16x32_bf16 v[12:15], v[164:167], v[212:215], v[12:15]
	v_mfma_f32_16x16x32_bf16 v[48:51], v[168:171], v[184:187], v[48:51]
	v_mfma_f32_16x16x32_bf16 v[40:43], v[176:179], v[184:187], v[40:43]
	v_mfma_f32_16x16x32_bf16 v[32:35], v[168:171], v[192:195], v[32:35]
	v_mfma_f32_16x16x32_bf16 v[24:27], v[176:179], v[192:195], v[24:27]
	v_mfma_f32_16x16x32_bf16 v[16:19], v[168:171], v[200:203], v[16:19]
	v_mfma_f32_16x16x32_bf16 v[8:11], v[176:179], v[200:203], v[8:11]
	v_mfma_f32_16x16x32_bf16 v[4:7], v[168:171], v[208:211], v[4:7]
	v_mfma_f32_16x16x32_bf16 v[0:3], v[176:179], v[208:211], v[0:3]
	v_mfma_f32_16x16x32_bf16 v[48:51], v[172:175], v[188:191], v[48:51]
	v_mfma_f32_16x16x32_bf16 v[40:43], v[180:183], v[188:191], v[40:43]
	v_mfma_f32_16x16x32_bf16 v[32:35], v[172:175], v[196:199], v[32:35]
	v_mfma_f32_16x16x32_bf16 v[24:27], v[180:183], v[196:199], v[24:27]
	v_mfma_f32_16x16x32_bf16 v[16:19], v[172:175], v[204:207], v[16:19]
	v_mfma_f32_16x16x32_bf16 v[8:11], v[180:183], v[204:207], v[8:11]
	v_mfma_f32_16x16x32_bf16 v[4:7], v[172:175], v[212:215], v[4:7]
	v_mfma_f32_16x16x32_bf16 v[0:3], v[180:183], v[212:215], v[0:3]
	s_barrier
	s_add_i32 s53, s53, 2
	s_add_u32 s20, s20, 0x100
	s_addc_u32 s21, s21, 0
	s_add_u32 s51, s51, 0x100
	s_addc_u32 s52, s52, 0
	s_cmp_gt_u32 s53, 29
	s_cbranch_scc0 .LBB0_228
	s_and_b64 vcc, exec, s[8:9]
	s_cbranch_vccz .LBB0_231
	s_barrier

; #define PG8_STAGE(bufoff, gbase, voff) do { _Pragma("unroll") for (int _i = 0; _i < 2; ++_i) \
;         __builtin_amdgcn_global_load_lds((const unsigned*)((const char*)(gbase) + (voff)[_i]), (PG8_LAS unsigned*)(lds + (bufoff) + ldsw + _i * 8192), 16, 0, 0); } while (0)
; #define PG8_LDA(dst, b, h) do { _Pragma("unroll") for (int m = 0; m < 4; ++m) _Pragma("unroll") for (int k = 0; k < 2; ++k) dst[m][k] = *(const PG8_LAS bf16x8*)(lds + PG8_SA(b, h) + aoff + m * 2048 + k * 1024); } while (0)
; #define PG8_LDB(dst, b, h) do { _Pragma("unroll") for (int n = 0; n < 2; ++n) _Pragma("unroll") for (int k = 0; k < 2; ++k) dst[n][k] = *(const PG8_LAS bf16x8*)(lds + PG8_SB(b, h) + boff + n * 2048 + k * 1024); } while (0)
; #define PG8_MMA(ai, bj, At, Bt) do { __builtin_amdgcn_s_setprio(1); _Pragma("unroll") for (int m = 0; m < 4; ++m) _Pragma("unroll") for (int n = 0; n < 2; ++n) _Pragma("unroll") for (int k = 0; k < 2; ++k) \
;         acc[ai][bj][m][n] = __builtin_amdgcn_mfma_f32_16x16x32_bf16(Bt[n][k], At[m][k], acc[ai][bj][m][n], 0, 0, 0); __builtin_amdgcn_s_setprio(0); } while (0)
; #define PG8_WAIT_V(n) asm volatile("s_waitcnt vmcnt(" #n ")" ::: "memory")
; #define PG8_WAIT_L(n) asm volatile("s_waitcnt lgkmcnt(" #n ")" ::: "memory")
; #define PG8_BAR __builtin_amdgcn_s_barrier()
; #define PG8_SCHED __builtin_amdgcn_sched_barrier(0)
; template <class Epi, class Sched, bool ALIGN_EPI = false, bool SP2 = false>
; __device__ __forceinline__ void gemm_phase(PG8_LAS unsigned char* lds, const Gemm g, const Sched& S, const Epi& E) {
;     ...
;             PG8_LDB(B0, 0, 0); PG8_LDB(B1, 0, 1); PG8_SCHED; PG8_LDA(At, 0, 0); PG8_STAGE(PG8_SA(1, 1), a1 + hstepA, voffA);
;             PG8_WAIT_V(8); PG8_WAIT_L(0); PG8_BAR; PG8_MMA(0, 0, At, B0); PG8_MMA(0, 1, At, B1); PG8_BAR; PG8_SCHED;
;             PG8_LDA(At, 0, 1); PG8_STAGE(PG8_SB(0, 0), b2, voffB); PG8_STAGE(PG8_SB(0, 1), b2 + hstepB, voffB); PG8_STAGE(PG8_SA(0, 0), a2, voffA);
;             PG8_WAIT_V(8); PG8_WAIT_L(0); PG8_BAR; PG8_MMA(1, 0, At, B0); PG8_MMA(1, 1, At, B1); PG8_BAR; PG8_SCHED;
;             PG8_LDB(B0, 1, 0); PG8_LDB(B1, 1, 1); PG8_SCHED; PG8_LDA(At, 1, 0); PG8_STAGE(PG8_SA(0, 1), a2 + hstepA, voffA);
.LBB0_2002:
	ds_read_b128 v[150:153], v159
	ds_read_b128 v[154:157], v159 offset:1024
	ds_read_b128 v[162:165], v159 offset:2048
	ds_read_b128 v[166:169], v159 offset:3072
	ds_read_b128 v[170:173], v160
	ds_read_b128 v[174:177], v160 offset:1024
	ds_read_b128 v[178:181], v160 offset:2048
	ds_read_b128 v[182:185], v160 offset:3072
	s_add_u32 s20, s4, 0xffe30080
	s_addc_u32 s21, s5, -1
	s_cmp_eq_u32 s54, 28
	s_cselect_b32 s23, s15, s21
	s_cselect_b32 s22, s14, s20
	s_cselect_b32 s21, s13, s53
	s_cselect_b32 s20, s51, s52
	v_lshl_add_u64 v[218:219], s[4:5], 0, v[142:143]
	s_add_i32 m0, s19, 0xc000
	ds_read_b128 v[186:189], v161
	ds_read_b128 v[190:193], v161 offset:1024
	ds_read_b128 v[194:197], v161 offset:2048
	ds_read_b128 v[198:201], v161 offset:3072
	ds_read_b128 v[202:205], v161 offset:4096
	ds_read_b128 v[206:209], v161 offset:5120
	ds_read_b128 v[210:213], v161 offset:6144
	ds_read_b128 v[214:217], v161 offset:7168
	global_load_lds_dwordx4 v[218:219], off
	v_lshl_add_u64 v[218:219], s[4:5], 0, v[144:145]
	s_add_i32 m0, s19, 0xe000
	s_nop 0
	global_load_lds_dwordx4 v[218:219], off
	s_waitcnt vmcnt(8)
	s_waitcnt lgkmcnt(0)
	s_barrier
	s_waitcnt lgkmcnt(0)
	v_mfma_f32_16x16x32_bf16 v[124:127], v[150:153], v[186:189], v[124:127]
	v_mfma_f32_16x16x32_bf16 v[120:123], v[162:165], v[186:189], v[120:123]
	v_mfma_f32_16x16x32_bf16 v[108:111], v[150:153], v[194:197], v[108:111]
	v_mfma_f32_16x16x32_bf16 v[104:107], v[162:165], v[194:197], v[104:107]
	v_mfma_f32_16x16x32_bf16 v[92:95], v[150:153], v[202:205], v[92:95]
	v_mfma_f32_16x16x32_bf16 v[88:91], v[162:165], v[202:205], v[88:91]
	v_mfma_f32_16x16x32_bf16 v[76:79], v[150:153], v[210:213], v[76:79]
	v_mfma_f32_16x16x32_bf16 v[72:75], v[162:165], v[210:213], v[72:75]
	v_mfma_f32_16x16x32_bf16 v[124:127], v[154:157], v[190:193], v[124:127]
	v_mfma_f32_16x16x32_bf16 v[120:123], v[166:169], v[190:193], v[120:123]
	v_mfma_f32_16x16x32_bf16 v[108:111], v[154:157], v[198:201], v[108:111]
	v_mfma_f32_16x16x32_bf16 v[104:107], v[166:169], v[198:201], v[104:107]
	v_mfma_f32_16x16x32_bf16 v[92:95], v[154:157], v[206:209], v[92:95]
	v_mfma_f32_16x16x32_bf16 v[88:91], v[166:169], v[206:209], v[88:91]
	v_mfma_f32_16x16x32_bf16 v[76:79], v[154:157], v[214:217], v[76:79]
	v_mfma_f32_16x16x32_bf16 v[72:75], v[166:169], v[214:217], v[72:75]
	v_mfma_f32_16x16x32_bf16 v[116:119], v[170:173], v[186:189], v[116:119]
	v_mfma_f32_16x16x32_bf16 v[112:115], v[178:181], v[186:189], v[112:115]
	v_mfma_f32_16x16x32_bf16 v[100:103], v[170:173], v[194:197], v[100:103]
	v_mfma_f32_16x16x32_bf16 v[96:99], v[178:181], v[194:197], v[96:99]
	v_mfma_f32_16x16x32_bf16 v[84:87], v[170:173], v[202:205], v[84:87]
	v_mfma_f32_16x16x32_bf16 v[80:83], v[178:181], v[202:205], v[80:83]
	v_mfma_f32_16x16x32_bf16 v[68:71], v[170:173], v[210:213], v[68:71]
	v_mfma_f32_16x16x32_bf16 v[64:67], v[178:181], v[210:213], v[64:67]
	v_mfma_f32_16x16x32_bf16 v[116:119], v[174:177], v[190:193], v[116:119]
	v_mfma_f32_16x16x32_bf16 v[112:115], v[182:185], v[190:193], v[112:115]
	v_mfma_f32_16x16x32_bf16 v[100:103], v[174:177], v[198:201], v[100:103]
	v_mfma_f32_16x16x32_bf16 v[96:99], v[182:185], v[198:201], v[96:99]
	v_mfma_f32_16x16x32_bf16 v[84:87], v[174:177], v[206:209], v[84:87]
	v_mfma_f32_16x16x32_bf16 v[80:83], v[182:185], v[206:209], v[80:83]
	v_mfma_f32_16x16x32_bf16 v[68:71], v[174:177], v[214:217], v[68:71]
	v_mfma_f32_16x16x32_bf16 v[64:67], v[182:185], v[214:217], v[64:67]
	s_barrier
	s_add_i32 s55, s41, s28
	v_lshl_add_u64 v[218:219], s[20:21], 0, v[134:135]
	s_mov_b32 m0, s55
	ds_read_b128 v[186:189], v161 offset:16384
	ds_read_b128 v[190:193], v161 offset:17408
	ds_read_b128 v[194:197], v161 offset:18432
	ds_read_b128 v[198:201], v161 offset:19456
	ds_read_b128 v[202:205], v161 offset:20480
	ds_read_b128 v[206:209], v161 offset:21504
	ds_read_b128 v[210:213], v161 offset:22528
	ds_read_b128 v[214:217], v161 offset:23552
	global_load_lds_dwordx4 v[218:219], off
	s_add_i32 m0, s55, 0x2000
	s_add_u32 s56, s20, 0x80000
	v_lshl_add_u64 v[220:221], s[20:21], 0, v[138:139]
	s_addc_u32 s57, s21, 0
	s_add_i32 s55, s42, s28
	global_load_lds_dwordx4 v[220:221], off
	v_lshl_add_u64 v[222:223], s[56:57], 0, v[134:135]
	s_mov_b32 m0, s55
	v_lshl_add_u64 v[224:225], s[22:23], 0, v[136:137]
	global_load_lds_dwordx4 v[222:223], off
	v_lshl_add_u64 v[222:223], s[56:57], 0, v[138:139]
	s_add_i32 m0, s55, 0x2000
	s_nop 0
	global_load_lds_dwordx4 v[222:223], off
	v_lshl_add_u64 v[222:223], s[22:23], 0, v[132:133]
	s_mov_b32 m0, s19
	s_nop 0
	global_load_lds_dwordx4 v[222:223], off
	s_mov_b32 m0, s29
	s_nop 0
	global_load_lds_dwordx4 v[224:225], off
	s_waitcnt vmcnt(8)
	s_waitcnt lgkmcnt(0)
	s_barrier
; #define PG8_STAGE(bufoff, gbase, voff) do { _Pragma("unroll") for (int _i = 0; _i < 2; ++_i) \
;         __builtin_amdgcn_global_load_lds((const unsigned*)((const char*)(gbase) + (voff)[_i]), (PG8_LAS unsigned*)(lds + (bufoff) + ldsw + _i * 8192), 16, 0, 0); } while (0)
; #define PG8_LDA(dst, b, h) do { _Pragma("unroll") for (int m = 0; m < 4; ++m) _Pragma("unroll") for (int k = 0; k < 2; ++k) dst[m][k] = *(const PG8_LAS bf16x8*)(lds + PG8_SA(b, h) + aoff + m * 2048 + k * 1024); } while (0)
; #define PG8_LDB(dst, b, h) do { _Pragma("unroll") for (int n = 0; n < 2; ++n) _Pragma("unroll") for (int k = 0; k < 2; ++k) dst[n][k] = *(const PG8_LAS bf16x8*)(lds + PG8_SB(b, h) + boff + n * 2048 + k * 1024); } while (0)
; #define PG8_MMA(ai, bj, At, Bt) do { __builtin_amdgcn_s_setprio(1); _Pragma("unroll") for (int m = 0; m < 4; ++m) _Pragma("unroll") for (int n = 0; n < 2; ++n) _Pragma("unroll") for (int k = 0; k < 2; ++k) \
;         acc[ai][bj][m][n] = __builtin_amdgcn_mfma_f32_16x16x32_bf16(Bt[n][k], At[m][k], acc[ai][bj][m][n], 0, 0, 0); __builtin_amdgcn_s_setprio(0); } while (0)
; #define PG8_WAIT_V(n) asm volatile("s_waitcnt vmcnt(" #n ")" ::: "memory")
; #define PG8_WAIT_L(n) asm volatile("s_waitcnt lgkmcnt(" #n ")" ::: "memory")
; #define PG8_BAR __builtin_amdgcn_s_barrier()
; #define PG8_SCHED __builtin_amdgcn_sched_barrier(0)
; template <class Epi, class Sched, bool ALIGN_EPI = false, bool SP2 = false>
; __device__ __forceinline__ void gemm_phase(PG8_LAS unsigned char* lds, const Gemm g, const Sched& S, const Epi& E) {
;     ...
;             PG8_WAIT_V(8); PG8_WAIT_L(0); PG8_BAR; PG8_MMA(0, 0, At, B0); PG8_MMA(0, 1, At, B1); PG8_BAR; PG8_SCHED;
;             PG8_LDA(At, 0, 1); PG8_STAGE(PG8_SB(0, 0), b2, voffB); PG8_STAGE(PG8_SB(0, 1), b2 + hstepB, voffB); PG8_STAGE(PG8_SA(0, 0), a2, voffA);
;             PG8_WAIT_V(8); PG8_WAIT_L(0); PG8_BAR; PG8_MMA(1, 0, At, B0); PG8_MMA(1, 1, At, B1); PG8_BAR; PG8_SCHED;
;             PG8_LDB(B0, 1, 0); PG8_LDB(B1, 1, 1); PG8_SCHED; PG8_LDA(At, 1, 0); PG8_STAGE(PG8_SA(0, 1), a2 + hstepA, voffA);
;             PG8_WAIT_V(8); PG8_WAIT_L(0); PG8_BAR; PG8_MMA(0, 0, At, B0); PG8_MMA(0, 1, At, B1); PG8_BAR; PG8_SCHED;
;             PG8_LDA(At, 1, 1); PG8_STAGE(PG8_SB(1, 0), b3, voffB); PG8_STAGE(PG8_SB(1, 1), b3 + hstepB, voffB); PG8_STAGE(PG8_SA(1, 0), a3, voffA);
	s_waitcnt lgkmcnt(0)
	v_mfma_f32_16x16x32_bf16 v[60:63], v[150:153], v[186:189], v[60:63]
	v_mfma_f32_16x16x32_bf16 v[56:59], v[162:165], v[186:189], v[56:59]
	v_mfma_f32_16x16x32_bf16 v[44:47], v[150:153], v[194:197], v[44:47]
	v_mfma_f32_16x16x32_bf16 v[40:43], v[162:165], v[194:197], v[40:43]
	v_mfma_f32_16x16x32_bf16 v[28:31], v[150:153], v[202:205], v[28:31]
	v_mfma_f32_16x16x32_bf16 v[24:27], v[162:165], v[202:205], v[24:27]
	v_mfma_f32_16x16x32_bf16 v[12:15], v[150:153], v[210:213], v[12:15]
	v_mfma_f32_16x16x32_bf16 v[8:11], v[162:165], v[210:213], v[8:11]
	v_mfma_f32_16x16x32_bf16 v[60:63], v[154:157], v[190:193], v[60:63]
	v_mfma_f32_16x16x32_bf16 v[56:59], v[166:169], v[190:193], v[56:59]
	v_mfma_f32_16x16x32_bf16 v[44:47], v[154:157], v[198:201], v[44:47]
	v_mfma_f32_16x16x32_bf16 v[40:43], v[166:169], v[198:201], v[40:43]
	v_mfma_f32_16x16x32_bf16 v[28:31], v[154:157], v[206:209], v[28:31]
	v_mfma_f32_16x16x32_bf16 v[24:27], v[166:169], v[206:209], v[24:27]
	v_mfma_f32_16x16x32_bf16 v[12:15], v[154:157], v[214:217], v[12:15]
	v_mfma_f32_16x16x32_bf16 v[8:11], v[166:169], v[214:217], v[8:11]
	v_mfma_f32_16x16x32_bf16 v[52:55], v[170:173], v[186:189], v[52:55]
	v_mfma_f32_16x16x32_bf16 v[48:51], v[178:181], v[186:189], v[48:51]
	v_mfma_f32_16x16x32_bf16 v[36:39], v[170:173], v[194:197], v[36:39]
	v_mfma_f32_16x16x32_bf16 v[32:35], v[178:181], v[194:197], v[32:35]
	v_mfma_f32_16x16x32_bf16 v[20:23], v[170:173], v[202:205], v[20:23]
	v_mfma_f32_16x16x32_bf16 v[16:19], v[178:181], v[202:205], v[16:19]
	v_mfma_f32_16x16x32_bf16 v[4:7], v[170:173], v[210:213], v[4:7]
	v_mfma_f32_16x16x32_bf16 v[0:3], v[178:181], v[210:213], v[0:3]
	v_mfma_f32_16x16x32_bf16 v[52:55], v[174:177], v[190:193], v[52:55]
	v_mfma_f32_16x16x32_bf16 v[48:51], v[182:185], v[190:193], v[48:51]
	v_mfma_f32_16x16x32_bf16 v[36:39], v[174:177], v[198:201], v[36:39]
	v_mfma_f32_16x16x32_bf16 v[32:35], v[182:185], v[198:201], v[32:35]
	v_mfma_f32_16x16x32_bf16 v[20:23], v[174:177], v[206:209], v[20:23]
	v_mfma_f32_16x16x32_bf16 v[16:19], v[182:185], v[206:209], v[16:19]
	v_mfma_f32_16x16x32_bf16 v[4:7], v[174:177], v[214:217], v[4:7]
	v_mfma_f32_16x16x32_bf16 v[0:3], v[182:185], v[214:217], v[0:3]
	s_barrier
	s_add_i32 s55, 0, 0x18000
	v_add_u32_e32 v140, s55, v131
	s_add_i32 s56, 0, 0x1c000
	ds_read_b128 v[150:153], v140
	ds_read_b128 v[154:157], v140 offset:1024
	ds_read_b128 v[162:165], v140 offset:2048
	ds_read_b128 v[166:169], v140 offset:3072
	v_add_u32_e32 v140, s56, v131
	ds_read_b128 v[170:173], v140
	ds_read_b128 v[174:177], v140 offset:1024
	ds_read_b128 v[178:181], v140 offset:2048
	ds_read_b128 v[182:185], v140 offset:3072
	s_add_u32 s22, s22, 0x1d0000
	s_addc_u32 s23, s23, 0
	s_mov_b32 m0, s30
	v_lshl_add_u64 v[226:227], s[22:23], 0, v[132:133]
	ds_read_b128 v[186:189], v161 offset:32768
	ds_read_b128 v[190:193], v161 offset:33792
	ds_read_b128 v[194:197], v161 offset:34816
	ds_read_b128 v[198:201], v161 offset:35840
	ds_read_b128 v[202:205], v161 offset:36864
	ds_read_b128 v[206:209], v161 offset:37888
	ds_read_b128 v[210:213], v161 offset:38912
	ds_read_b128 v[214:217], v161 offset:39936
	global_load_lds_dwordx4 v[226:227], off
	v_lshl_add_u64 v[226:227], s[22:23], 0, v[136:137]
	s_mov_b32 m0, s31
	s_nop 0
	global_load_lds_dwordx4 v[226:227], off
	s_waitcnt vmcnt(8)
	s_waitcnt lgkmcnt(0)
	s_barrier
	s_waitcnt lgkmcnt(0)
	v_mfma_f32_16x16x32_bf16 v[124:127], v[150:153], v[186:189], v[124:127]
	v_mfma_f32_16x16x32_bf16 v[120:123], v[162:165], v[186:189], v[120:123]
	v_mfma_f32_16x16x32_bf16 v[108:111], v[150:153], v[194:197], v[108:111]
	v_mfma_f32_16x16x32_bf16 v[104:107], v[162:165], v[194:197], v[104:107]
	v_mfma_f32_16x16x32_bf16 v[92:95], v[150:153], v[202:205], v[92:95]
	v_mfma_f32_16x16x32_bf16 v[88:91], v[162:165], v[202:205], v[88:91]
	v_mfma_f32_16x16x32_bf16 v[76:79], v[150:153], v[210:213], v[76:79]
	v_mfma_f32_16x16x32_bf16 v[72:75], v[162:165], v[210:213], v[72:75]
	v_mfma_f32_16x16x32_bf16 v[124:127], v[154:157], v[190:193], v[124:127]
	v_mfma_f32_16x16x32_bf16 v[120:123], v[166:169], v[190:193], v[120:123]
	v_mfma_f32_16x16x32_bf16 v[108:111], v[154:157], v[198:201], v[108:111]
	v_mfma_f32_16x16x32_bf16 v[104:107], v[166:169], v[198:201], v[104:107]
	v_mfma_f32_16x16x32_bf16 v[92:95], v[154:157], v[206:209], v[92:95]
	v_mfma_f32_16x16x32_bf16 v[88:91], v[166:169], v[206:209], v[88:91]
	v_mfma_f32_16x16x32_bf16 v[76:79], v[154:157], v[214:217], v[76:79]
	v_mfma_f32_16x16x32_bf16 v[72:75], v[166:169], v[214:217], v[72:75]
	v_mfma_f32_16x16x32_bf16 v[116:119], v[170:173], v[186:189], v[116:119]
	v_mfma_f32_16x16x32_bf16 v[112:115], v[178:181], v[186:189], v[112:115]
	v_mfma_f32_16x16x32_bf16 v[100:103], v[170:173], v[194:197], v[100:103]
	v_mfma_f32_16x16x32_bf16 v[96:99], v[178:181], v[194:197], v[96:99]
	v_mfma_f32_16x16x32_bf16 v[84:87], v[170:173], v[202:205], v[84:87]
	v_mfma_f32_16x16x32_bf16 v[80:83], v[178:181], v[202:205], v[80:83]
	v_mfma_f32_16x16x32_bf16 v[68:71], v[170:173], v[210:213], v[68:71]
	v_mfma_f32_16x16x32_bf16 v[64:67], v[178:181], v[210:213], v[64:67]
	v_mfma_f32_16x16x32_bf16 v[116:119], v[174:177], v[190:193], v[116:119]
	v_mfma_f32_16x16x32_bf16 v[112:115], v[182:185], v[190:193], v[112:115]
	v_mfma_f32_16x16x32_bf16 v[100:103], v[174:177], v[198:201], v[100:103]
	v_mfma_f32_16x16x32_bf16 v[96:99], v[182:185], v[198:201], v[96:99]
	v_mfma_f32_16x16x32_bf16 v[84:87], v[174:177], v[206:209], v[84:87]
	v_mfma_f32_16x16x32_bf16 v[80:83], v[182:185], v[206:209], v[80:83]
	v_mfma_f32_16x16x32_bf16 v[68:71], v[174:177], v[214:217], v[68:71]
	v_mfma_f32_16x16x32_bf16 v[64:67], v[182:185], v[214:217], v[64:67]
	s_barrier
; #define PG8_STAGE(bufoff, gbase, voff) do { _Pragma("unroll") for (int _i = 0; _i < 2; ++_i) \
;         __builtin_amdgcn_global_load_lds((const unsigned*)((const char*)(gbase) + (voff)[_i]), (PG8_LAS unsigned*)(lds + (bufoff) + ldsw + _i * 8192), 16, 0, 0); } while (0)
; #define PG8_LDA(dst, b, h) do { _Pragma("unroll") for (int m = 0; m < 4; ++m) _Pragma("unroll") for (int k = 0; k < 2; ++k) dst[m][k] = *(const PG8_LAS bf16x8*)(lds + PG8_SA(b, h) + aoff + m * 2048 + k * 1024); } while (0)
; #define PG8_LDB(dst, b, h) do { _Pragma("unroll") for (int n = 0; n < 2; ++n) _Pragma("unroll") for (int k = 0; k < 2; ++k) dst[n][k] = *(const PG8_LAS bf16x8*)(lds + PG8_SB(b, h) + boff + n * 2048 + k * 1024); } while (0)
; #define PG8_MMA(ai, bj, At, Bt) do { __builtin_amdgcn_s_setprio(1); _Pragma("unroll") for (int m = 0; m < 4; ++m) _Pragma("unroll") for (int n = 0; n < 2; ++n) _Pragma("unroll") for (int k = 0; k < 2; ++k) \
;         acc[ai][bj][m][n] = __builtin_amdgcn_mfma_f32_16x16x32_bf16(Bt[n][k], At[m][k], acc[ai][bj][m][n], 0, 0, 0); __builtin_amdgcn_s_setprio(0); } while (0)
; #define PG8_WAIT_V(n) asm volatile("s_waitcnt vmcnt(" #n ")" ::: "memory")
; #define PG8_WAIT_L(n) asm volatile("s_waitcnt lgkmcnt(" #n ")" ::: "memory")
; #define PG8_BAR __builtin_amdgcn_s_barrier()
; #define PG8_SCHED __builtin_amdgcn_sched_barrier(0)
; template <class Epi, class Sched, bool ALIGN_EPI = false, bool SP2 = false>
; __device__ __forceinline__ void gemm_phase(PG8_LAS unsigned char* lds, const Gemm g, const Sched& S, const Epi& E) {
;     ...
;             PG8_LDB(B0, 1, 0); PG8_LDB(B1, 1, 1); PG8_SCHED; PG8_LDA(At, 1, 0); PG8_STAGE(PG8_SA(0, 1), a2 + hstepA, voffA);
;             PG8_WAIT_V(8); PG8_WAIT_L(0); PG8_BAR; PG8_MMA(0, 0, At, B0); PG8_MMA(0, 1, At, B1); PG8_BAR; PG8_SCHED;
;             PG8_LDA(At, 1, 1); PG8_STAGE(PG8_SB(1, 0), b3, voffB); PG8_STAGE(PG8_SB(1, 1), b3 + hstepB, voffB); PG8_STAGE(PG8_SA(1, 0), a3, voffA);
;             PG8_WAIT_V(8); PG8_WAIT_L(0); PG8_BAR; PG8_MMA(1, 0, At, B0); PG8_MMA(1, 1, At, B1); PG8_BAR; PG8_SCHED;
	s_add_i32 s22, s55, s28
	v_lshl_add_u64 v[218:219], v[218:219], 0, s[8:9]
	s_mov_b32 m0, s22
	ds_read_b128 v[186:189], v161 offset:49152
	ds_read_b128 v[190:193], v161 offset:50176
	ds_read_b128 v[194:197], v161 offset:51200
	ds_read_b128 v[198:201], v161 offset:52224
	ds_read_b128 v[202:205], v161 offset:53248
	ds_read_b128 v[206:209], v161 offset:54272
	ds_read_b128 v[210:213], v161 offset:55296
	ds_read_b128 v[214:217], v161 offset:56320
	global_load_lds_dwordx4 v[218:219], off
	s_add_i32 m0, s22, 0x2000
	s_add_u32 s20, s20, 0x80080
	v_lshl_add_u64 v[218:219], v[220:221], 0, s[8:9]
	s_addc_u32 s21, s21, 0
	s_add_i32 s22, s56, s28
	global_load_lds_dwordx4 v[218:219], off
	v_lshl_add_u64 v[218:219], s[20:21], 0, v[134:135]
	s_mov_b32 m0, s22
	s_nop 0
	global_load_lds_dwordx4 v[218:219], off
	v_lshl_add_u64 v[218:219], s[20:21], 0, v[138:139]
	s_add_i32 m0, s22, 0x2000
	s_nop 0
	global_load_lds_dwordx4 v[218:219], off
	v_lshl_add_u64 v[218:219], v[222:223], 0, s[8:9]
	s_mov_b32 m0, s35
	s_nop 0
	global_load_lds_dwordx4 v[218:219], off
	v_lshl_add_u64 v[218:219], v[224:225], 0, s[8:9]
	s_mov_b32 m0, s36
	s_nop 0
	global_load_lds_dwordx4 v[218:219], off
	s_waitcnt vmcnt(8)
	s_waitcnt lgkmcnt(0)
	s_barrier
	s_waitcnt lgkmcnt(0)
	v_mfma_f32_16x16x32_bf16 v[60:63], v[150:153], v[186:189], v[60:63]
	v_mfma_f32_16x16x32_bf16 v[56:59], v[162:165], v[186:189], v[56:59]
	v_mfma_f32_16x16x32_bf16 v[44:47], v[150:153], v[194:197], v[44:47]
	v_mfma_f32_16x16x32_bf16 v[40:43], v[162:165], v[194:197], v[40:43]
	v_mfma_f32_16x16x32_bf16 v[28:31], v[150:153], v[202:205], v[28:31]
	v_mfma_f32_16x16x32_bf16 v[24:27], v[162:165], v[202:205], v[24:27]
	v_mfma_f32_16x16x32_bf16 v[12:15], v[150:153], v[210:213], v[12:15]
	v_mfma_f32_16x16x32_bf16 v[8:11], v[162:165], v[210:213], v[8:11]
	v_mfma_f32_16x16x32_bf16 v[60:63], v[154:157], v[190:193], v[60:63]
	v_mfma_f32_16x16x32_bf16 v[56:59], v[166:169], v[190:193], v[56:59]
	v_mfma_f32_16x16x32_bf16 v[44:47], v[154:157], v[198:201], v[44:47]
	v_mfma_f32_16x16x32_bf16 v[40:43], v[166:169], v[198:201], v[40:43]
	v_mfma_f32_16x16x32_bf16 v[28:31], v[154:157], v[206:209], v[28:31]
	v_mfma_f32_16x16x32_bf16 v[24:27], v[166:169], v[206:209], v[24:27]
	v_mfma_f32_16x16x32_bf16 v[12:15], v[154:157], v[214:217], v[12:15]
	v_mfma_f32_16x16x32_bf16 v[8:11], v[166:169], v[214:217], v[8:11]
	v_mfma_f32_16x16x32_bf16 v[52:55], v[170:173], v[186:189], v[52:55]
	v_mfma_f32_16x16x32_bf16 v[48:51], v[178:181], v[186:189], v[48:51]
	v_mfma_f32_16x16x32_bf16 v[36:39], v[170:173], v[194:197], v[36:39]
	v_mfma_f32_16x16x32_bf16 v[32:35], v[178:181], v[194:197], v[32:35]
	v_mfma_f32_16x16x32_bf16 v[20:23], v[170:173], v[202:205], v[20:23]
	v_mfma_f32_16x16x32_bf16 v[16:19], v[178:181], v[202:205], v[16:19]
	v_mfma_f32_16x16x32_bf16 v[4:7], v[170:173], v[210:213], v[4:7]
	v_mfma_f32_16x16x32_bf16 v[0:3], v[178:181], v[210:213], v[0:3]
	v_mfma_f32_16x16x32_bf16 v[52:55], v[174:177], v[190:193], v[52:55]
	v_mfma_f32_16x16x32_bf16 v[48:51], v[182:185], v[190:193], v[48:51]
	v_mfma_f32_16x16x32_bf16 v[36:39], v[174:177], v[198:201], v[36:39]
	v_mfma_f32_16x16x32_bf16 v[32:35], v[182:185], v[198:201], v[32:35]
	v_mfma_f32_16x16x32_bf16 v[20:23], v[174:177], v[206:209], v[20:23]
	v_mfma_f32_16x16x32_bf16 v[16:19], v[182:185], v[206:209], v[16:19]
	v_mfma_f32_16x16x32_bf16 v[4:7], v[174:177], v[214:217], v[4:7]
	v_mfma_f32_16x16x32_bf16 v[0:3], v[182:185], v[214:217], v[0:3]
	s_barrier
	s_add_i32 s54, s54, 2
	s_add_u32 s4, s4, 0x100
	s_addc_u32 s5, s5, 0
	s_add_u32 s52, s52, 0x100
	s_addc_u32 s53, s53, 0
	s_cmp_gt_u32 s54, 29
	s_cbranch_scc0 .LBB0_2002
	s_and_b64 vcc, exec, s[10:11]
	s_cbranch_vccz .LBB0_2005
	s_barrier

; #define PG8_STAGE(bufoff, gbase, voff) do { _Pragma("unroll") for (int _i = 0; _i < 2; ++_i) \
;         __builtin_amdgcn_global_load_lds((const unsigned*)((const char*)(gbase) + (voff)[_i]), (PG8_LAS unsigned*)(lds + (bufoff) + ldsw + _i * 8192), 16, 0, 0); } while (0)
; #define PG8_LDA(dst, b, h) do { _Pragma("unroll") for (int m = 0; m < 4; ++m) _Pragma("unroll") for (int k = 0; k < 2; ++k) dst[m][k] = *(const PG8_LAS bf16x8*)(lds + PG8_SA(b, h) + aoff + m * 2048 + k * 1024); } while (0)
; #define PG8_LDB(dst, b, h) do { _Pragma("unroll") for (int n = 0; n < 2; ++n) _Pragma("unroll") for (int k = 0; k < 2; ++k) dst[n][k] = *(const PG8_LAS bf16x8*)(lds + PG8_SB(b, h) + boff + n * 2048 + k * 1024); } while (0)
; #define PG8_MMA(ai, bj, At, Bt) do { __builtin_amdgcn_s_setprio(1); _Pragma("unroll") for (int m = 0; m < 4; ++m) _Pragma("unroll") for (int n = 0; n < 2; ++n) _Pragma("unroll") for (int k = 0; k < 2; ++k) \
;         acc[ai][bj][m][n] = __builtin_amdgcn_mfma_f32_16x16x32_bf16(Bt[n][k], At[m][k], acc[ai][bj][m][n], 0, 0, 0); __builtin_amdgcn_s_setprio(0); } while (0)
; #define PG8_WAIT_V(n) asm volatile("s_waitcnt vmcnt(" #n ")" ::: "memory")
; #define PG8_WAIT_L(n) asm volatile("s_waitcnt lgkmcnt(" #n ")" ::: "memory")
; #define PG8_BAR __builtin_amdgcn_s_barrier()
; #define PG8_SCHED __builtin_amdgcn_sched_barrier(0)
; template <class Epi, class Sched, bool ALIGN_EPI = false, bool SP2 = false>
; __device__ __forceinline__ void gemm_phase(PG8_LAS unsigned char* lds, const Gemm g, const Sched& S, const Epi& E) {
;     ...
;             PG8_LDB(B0, 0, 0); PG8_LDB(B1, 0, 1); PG8_SCHED; PG8_LDA(At, 0, 0); PG8_STAGE(PG8_SA(1, 1), a1 + hstepA, voffA);
;             PG8_WAIT_V(8); PG8_WAIT_L(0); PG8_BAR; PG8_MMA(0, 0, At, B0); PG8_MMA(0, 1, At, B1); PG8_BAR; PG8_SCHED;
;             PG8_LDA(At, 0, 1); PG8_STAGE(PG8_SB(0, 0), b2, voffB); PG8_STAGE(PG8_SB(0, 1), b2 + hstepB, voffB); PG8_STAGE(PG8_SA(0, 0), a2, voffA);
;             PG8_WAIT_V(8); PG8_WAIT_L(0); PG8_BAR; PG8_MMA(1, 0, At, B0); PG8_MMA(1, 1, At, B1); PG8_BAR; PG8_SCHED;
;             PG8_LDB(B0, 1, 0); PG8_LDB(B1, 1, 1); PG8_SCHED; PG8_LDA(At, 1, 0); PG8_STAGE(PG8_SA(0, 1), a2 + hstepA, voffA);
.LBB0_2208:
	ds_read_b128 v[162:165], v149
	ds_read_b128 v[166:169], v149 offset:1024
	ds_read_b128 v[170:173], v149 offset:2048
	ds_read_b128 v[174:177], v149 offset:3072
	ds_read_b128 v[178:181], v151
	ds_read_b128 v[182:185], v151 offset:1024
	ds_read_b128 v[186:189], v151 offset:2048
	ds_read_b128 v[190:193], v151 offset:3072
	s_add_u32 s12, s8, 0xfff80080
	s_addc_u32 s13, s9, -1
	s_cmp_eq_u32 s22, 28
	s_cselect_b32 s15, s11, s13
	s_cselect_b32 s14, s17, s12
	s_cselect_b32 s13, s18, s21
	s_cselect_b32 s12, s19, s20
	v_lshl_add_u64 v[226:227], s[8:9], 0, v[154:155]
	s_add_i32 m0, s69, 0xc000
	ds_read_b128 v[194:197], v153
	ds_read_b128 v[198:201], v153 offset:1024
	ds_read_b128 v[202:205], v153 offset:2048
	ds_read_b128 v[206:209], v153 offset:3072
	ds_read_b128 v[210:213], v153 offset:4096
	ds_read_b128 v[214:217], v153 offset:5120
	ds_read_b128 v[218:221], v153 offset:6144
	ds_read_b128 v[222:225], v153 offset:7168
	global_load_lds_dwordx4 v[226:227], off
	v_lshl_add_u64 v[226:227], s[8:9], 0, v[156:157]
	s_add_i32 m0, s69, 0xe000
	s_nop 0
	global_load_lds_dwordx4 v[226:227], off
	s_waitcnt vmcnt(8)
	s_waitcnt lgkmcnt(0)
	s_barrier
	s_waitcnt lgkmcnt(0)
	v_mfma_f32_16x16x32_bf16 v[60:63], v[162:165], v[194:197], v[60:63]
	v_mfma_f32_16x16x32_bf16 v[56:59], v[170:173], v[194:197], v[56:59]
	v_mfma_f32_16x16x32_bf16 v[108:111], v[162:165], v[202:205], v[108:111]
	v_mfma_f32_16x16x32_bf16 v[92:95], v[170:173], v[202:205], v[92:95]
	v_mfma_f32_16x16x32_bf16 v[100:103], v[162:165], v[210:213], v[100:103]
	v_mfma_f32_16x16x32_bf16 v[84:87], v[170:173], v[210:213], v[84:87]
	v_mfma_f32_16x16x32_bf16 v[44:47], v[162:165], v[218:221], v[44:47]
	v_mfma_f32_16x16x32_bf16 v[40:43], v[170:173], v[218:221], v[40:43]
	v_mfma_f32_16x16x32_bf16 v[60:63], v[166:169], v[198:201], v[60:63]
	v_mfma_f32_16x16x32_bf16 v[56:59], v[174:177], v[198:201], v[56:59]
	v_mfma_f32_16x16x32_bf16 v[108:111], v[166:169], v[206:209], v[108:111]
	v_mfma_f32_16x16x32_bf16 v[92:95], v[174:177], v[206:209], v[92:95]
	v_mfma_f32_16x16x32_bf16 v[100:103], v[166:169], v[214:217], v[100:103]
	v_mfma_f32_16x16x32_bf16 v[84:87], v[174:177], v[214:217], v[84:87]
	v_mfma_f32_16x16x32_bf16 v[44:47], v[166:169], v[222:225], v[44:47]
	v_mfma_f32_16x16x32_bf16 v[40:43], v[174:177], v[222:225], v[40:43]
	v_mfma_f32_16x16x32_bf16 v[52:55], v[178:181], v[194:197], v[52:55]
	v_mfma_f32_16x16x32_bf16 v[48:51], v[186:189], v[194:197], v[48:51]
	v_mfma_f32_16x16x32_bf16 v[104:107], v[178:181], v[202:205], v[104:107]
	v_mfma_f32_16x16x32_bf16 v[88:91], v[186:189], v[202:205], v[88:91]
	v_mfma_f32_16x16x32_bf16 v[96:99], v[178:181], v[210:213], v[96:99]
	v_mfma_f32_16x16x32_bf16 v[80:83], v[186:189], v[210:213], v[80:83]
	v_mfma_f32_16x16x32_bf16 v[36:39], v[178:181], v[218:221], v[36:39]
	v_mfma_f32_16x16x32_bf16 v[32:35], v[186:189], v[218:221], v[32:35]
	v_mfma_f32_16x16x32_bf16 v[52:55], v[182:185], v[198:201], v[52:55]
	v_mfma_f32_16x16x32_bf16 v[48:51], v[190:193], v[198:201], v[48:51]
	v_mfma_f32_16x16x32_bf16 v[104:107], v[182:185], v[206:209], v[104:107]
	v_mfma_f32_16x16x32_bf16 v[88:91], v[190:193], v[206:209], v[88:91]
	v_mfma_f32_16x16x32_bf16 v[96:99], v[182:185], v[214:217], v[96:99]
	v_mfma_f32_16x16x32_bf16 v[80:83], v[190:193], v[214:217], v[80:83]
	v_mfma_f32_16x16x32_bf16 v[36:39], v[182:185], v[222:225], v[36:39]
	v_mfma_f32_16x16x32_bf16 v[32:35], v[190:193], v[222:225], v[32:35]
	s_barrier
	s_add_i32 s23, s1, s2
	v_lshl_add_u64 v[226:227], s[12:13], 0, v[134:135]
	s_mov_b32 m0, s23
	ds_read_b128 v[194:197], v153 offset:16384
	ds_read_b128 v[198:201], v153 offset:17408
	ds_read_b128 v[202:205], v153 offset:18432
	ds_read_b128 v[206:209], v153 offset:19456
	ds_read_b128 v[210:213], v153 offset:20480
	ds_read_b128 v[214:217], v153 offset:21504
	ds_read_b128 v[218:221], v153 offset:22528
	ds_read_b128 v[222:225], v153 offset:23552
	global_load_lds_dwordx4 v[226:227], off
	s_add_i32 m0, s23, 0x2000
	s_add_u32 s24, s12, 0x80000
	v_lshl_add_u64 v[228:229], s[12:13], 0, v[130:131]
	s_addc_u32 s25, s13, 0
	s_add_i32 s23, s4, s2
	global_load_lds_dwordx4 v[228:229], off
	v_lshl_add_u64 v[230:231], s[24:25], 0, v[134:135]
	s_mov_b32 m0, s23
	v_lshl_add_u64 v[232:233], s[14:15], 0, v[132:133]
	global_load_lds_dwordx4 v[230:231], off
	v_lshl_add_u64 v[230:231], s[24:25], 0, v[130:131]
	s_add_i32 m0, s23, 0x2000
	s_nop 0
	global_load_lds_dwordx4 v[230:231], off
	v_lshl_add_u64 v[230:231], s[14:15], 0, v[136:137]
	s_mov_b32 m0, s69
	s_nop 0
	global_load_lds_dwordx4 v[230:231], off
	s_mov_b32 m0, s3
	s_nop 0
	global_load_lds_dwordx4 v[232:233], off
	s_waitcnt vmcnt(8)
	s_waitcnt lgkmcnt(0)
	s_barrier
; #define PG8_STAGE(bufoff, gbase, voff) do { _Pragma("unroll") for (int _i = 0; _i < 2; ++_i) \
;         __builtin_amdgcn_global_load_lds((const unsigned*)((const char*)(gbase) + (voff)[_i]), (PG8_LAS unsigned*)(lds + (bufoff) + ldsw + _i * 8192), 16, 0, 0); } while (0)
; #define PG8_LDA(dst, b, h) do { _Pragma("unroll") for (int m = 0; m < 4; ++m) _Pragma("unroll") for (int k = 0; k < 2; ++k) dst[m][k] = *(const PG8_LAS bf16x8*)(lds + PG8_SA(b, h) + aoff + m * 2048 + k * 1024); } while (0)
; #define PG8_LDB(dst, b, h) do { _Pragma("unroll") for (int n = 0; n < 2; ++n) _Pragma("unroll") for (int k = 0; k < 2; ++k) dst[n][k] = *(const PG8_LAS bf16x8*)(lds + PG8_SB(b, h) + boff + n * 2048 + k * 1024); } while (0)
; #define PG8_MMA(ai, bj, At, Bt) do { __builtin_amdgcn_s_setprio(1); _Pragma("unroll") for (int m = 0; m < 4; ++m) _Pragma("unroll") for (int n = 0; n < 2; ++n) _Pragma("unroll") for (int k = 0; k < 2; ++k) \
;         acc[ai][bj][m][n] = __builtin_amdgcn_mfma_f32_16x16x32_bf16(Bt[n][k], At[m][k], acc[ai][bj][m][n], 0, 0, 0); __builtin_amdgcn_s_setprio(0); } while (0)
; #define PG8_WAIT_V(n) asm volatile("s_waitcnt vmcnt(" #n ")" ::: "memory")
; #define PG8_WAIT_L(n) asm volatile("s_waitcnt lgkmcnt(" #n ")" ::: "memory")
; #define PG8_BAR __builtin_amdgcn_s_barrier()
; #define PG8_SCHED __builtin_amdgcn_sched_barrier(0)
; template <class Epi, class Sched, bool ALIGN_EPI = false, bool SP2 = false>
; __device__ __forceinline__ void gemm_phase(PG8_LAS unsigned char* lds, const Gemm g, const Sched& S, const Epi& E) {
;     ...
;             PG8_WAIT_V(8); PG8_WAIT_L(0); PG8_BAR; PG8_MMA(0, 0, At, B0); PG8_MMA(0, 1, At, B1); PG8_BAR; PG8_SCHED;
;             PG8_LDA(At, 0, 1); PG8_STAGE(PG8_SB(0, 0), b2, voffB); PG8_STAGE(PG8_SB(0, 1), b2 + hstepB, voffB); PG8_STAGE(PG8_SA(0, 0), a2, voffA);
;             PG8_WAIT_V(8); PG8_WAIT_L(0); PG8_BAR; PG8_MMA(1, 0, At, B0); PG8_MMA(1, 1, At, B1); PG8_BAR; PG8_SCHED;
;             PG8_LDB(B0, 1, 0); PG8_LDB(B1, 1, 1); PG8_SCHED; PG8_LDA(At, 1, 0); PG8_STAGE(PG8_SA(0, 1), a2 + hstepA, voffA);
;             PG8_WAIT_V(8); PG8_WAIT_L(0); PG8_BAR; PG8_MMA(0, 0, At, B0); PG8_MMA(0, 1, At, B1); PG8_BAR; PG8_SCHED;
;             PG8_LDA(At, 1, 1); PG8_STAGE(PG8_SB(1, 0), b3, voffB); PG8_STAGE(PG8_SB(1, 1), b3 + hstepB, voffB); PG8_STAGE(PG8_SA(1, 0), a3, voffA);
	s_waitcnt lgkmcnt(0)
	v_mfma_f32_16x16x32_bf16 v[28:31], v[162:165], v[194:197], v[28:31]
	v_mfma_f32_16x16x32_bf16 v[24:27], v[170:173], v[194:197], v[24:27]
	v_mfma_f32_16x16x32_bf16 v[124:127], v[162:165], v[202:205], v[124:127]
	v_mfma_f32_16x16x32_bf16 v[76:79], v[170:173], v[202:205], v[76:79]
	v_mfma_f32_16x16x32_bf16 v[116:119], v[162:165], v[210:213], v[116:119]
	v_mfma_f32_16x16x32_bf16 v[68:71], v[170:173], v[210:213], v[68:71]
	v_mfma_f32_16x16x32_bf16 v[12:15], v[162:165], v[218:221], v[12:15]
	v_mfma_f32_16x16x32_bf16 v[8:11], v[170:173], v[218:221], v[8:11]
	v_mfma_f32_16x16x32_bf16 v[28:31], v[166:169], v[198:201], v[28:31]
	v_mfma_f32_16x16x32_bf16 v[24:27], v[174:177], v[198:201], v[24:27]
	v_mfma_f32_16x16x32_bf16 v[124:127], v[166:169], v[206:209], v[124:127]
	v_mfma_f32_16x16x32_bf16 v[76:79], v[174:177], v[206:209], v[76:79]
	v_mfma_f32_16x16x32_bf16 v[116:119], v[166:169], v[214:217], v[116:119]
	v_mfma_f32_16x16x32_bf16 v[68:71], v[174:177], v[214:217], v[68:71]
	v_mfma_f32_16x16x32_bf16 v[12:15], v[166:169], v[222:225], v[12:15]
	v_mfma_f32_16x16x32_bf16 v[8:11], v[174:177], v[222:225], v[8:11]
	v_mfma_f32_16x16x32_bf16 v[20:23], v[178:181], v[194:197], v[20:23]
	v_mfma_f32_16x16x32_bf16 v[16:19], v[186:189], v[194:197], v[16:19]
	v_mfma_f32_16x16x32_bf16 v[120:123], v[178:181], v[202:205], v[120:123]
	v_mfma_f32_16x16x32_bf16 v[72:75], v[186:189], v[202:205], v[72:75]
	v_mfma_f32_16x16x32_bf16 v[112:115], v[178:181], v[210:213], v[112:115]
	v_mfma_f32_16x16x32_bf16 v[64:67], v[186:189], v[210:213], v[64:67]
	v_mfma_f32_16x16x32_bf16 v[4:7], v[178:181], v[218:221], v[4:7]
	v_mfma_f32_16x16x32_bf16 v[0:3], v[186:189], v[218:221], v[0:3]
	v_mfma_f32_16x16x32_bf16 v[20:23], v[182:185], v[198:201], v[20:23]
	v_mfma_f32_16x16x32_bf16 v[16:19], v[190:193], v[198:201], v[16:19]
	v_mfma_f32_16x16x32_bf16 v[120:123], v[182:185], v[206:209], v[120:123]
	v_mfma_f32_16x16x32_bf16 v[72:75], v[190:193], v[206:209], v[72:75]
	v_mfma_f32_16x16x32_bf16 v[112:115], v[182:185], v[214:217], v[112:115]
	v_mfma_f32_16x16x32_bf16 v[64:67], v[190:193], v[214:217], v[64:67]
	v_mfma_f32_16x16x32_bf16 v[4:7], v[182:185], v[222:225], v[4:7]
	v_mfma_f32_16x16x32_bf16 v[0:3], v[190:193], v[222:225], v[0:3]
	s_barrier
	s_add_i32 s23, 0, 0x18000
	s_add_i32 s24, 0, 0x1c000
	v_add_u32_e32 v174, s23, v139
	v_add_u32_e32 v190, s24, v139
	ds_read_b128 v[162:165], v174
	ds_read_b128 v[166:169], v174 offset:1024
	ds_read_b128 v[170:173], v174 offset:2048
	ds_read_b128 v[174:177], v174 offset:3072
	ds_read_b128 v[178:181], v190
	ds_read_b128 v[182:185], v190 offset:1024
	ds_read_b128 v[186:189], v190 offset:2048
	ds_read_b128 v[190:193], v190 offset:3072
	s_add_u32 s14, s14, 0x80000
	s_addc_u32 s15, s15, 0
	s_mov_b32 m0, s33
	v_lshl_add_u64 v[234:235], s[14:15], 0, v[136:137]
	ds_read_b128 v[194:197], v153 offset:32768
	ds_read_b128 v[198:201], v153 offset:33792
	ds_read_b128 v[202:205], v153 offset:34816
	ds_read_b128 v[206:209], v153 offset:35840
	ds_read_b128 v[210:213], v153 offset:36864
	ds_read_b128 v[214:217], v153 offset:37888
	ds_read_b128 v[218:221], v153 offset:38912
	ds_read_b128 v[222:225], v153 offset:39936
	global_load_lds_dwordx4 v[234:235], off
	v_lshl_add_u64 v[234:235], s[14:15], 0, v[132:133]
	s_mov_b32 m0, s72
	s_nop 0
	global_load_lds_dwordx4 v[234:235], off
	s_waitcnt vmcnt(8)
	s_waitcnt lgkmcnt(0)
	s_barrier
	s_waitcnt lgkmcnt(0)
	v_mfma_f32_16x16x32_bf16 v[60:63], v[162:165], v[194:197], v[60:63]
	v_mfma_f32_16x16x32_bf16 v[56:59], v[170:173], v[194:197], v[56:59]
	v_mfma_f32_16x16x32_bf16 v[108:111], v[162:165], v[202:205], v[108:111]
	v_mfma_f32_16x16x32_bf16 v[92:95], v[170:173], v[202:205], v[92:95]
	v_mfma_f32_16x16x32_bf16 v[100:103], v[162:165], v[210:213], v[100:103]
	v_mfma_f32_16x16x32_bf16 v[84:87], v[170:173], v[210:213], v[84:87]
	v_mfma_f32_16x16x32_bf16 v[44:47], v[162:165], v[218:221], v[44:47]
	v_mfma_f32_16x16x32_bf16 v[40:43], v[170:173], v[218:221], v[40:43]
	v_mfma_f32_16x16x32_bf16 v[60:63], v[166:169], v[198:201], v[60:63]
	v_mfma_f32_16x16x32_bf16 v[56:59], v[174:177], v[198:201], v[56:59]
	v_mfma_f32_16x16x32_bf16 v[108:111], v[166:169], v[206:209], v[108:111]
	v_mfma_f32_16x16x32_bf16 v[92:95], v[174:177], v[206:209], v[92:95]
	v_mfma_f32_16x16x32_bf16 v[100:103], v[166:169], v[214:217], v[100:103]
	v_mfma_f32_16x16x32_bf16 v[84:87], v[174:177], v[214:217], v[84:87]
	v_mfma_f32_16x16x32_bf16 v[44:47], v[166:169], v[222:225], v[44:47]
	v_mfma_f32_16x16x32_bf16 v[40:43], v[174:177], v[222:225], v[40:43]
	v_mfma_f32_16x16x32_bf16 v[52:55], v[178:181], v[194:197], v[52:55]
	v_mfma_f32_16x16x32_bf16 v[48:51], v[186:189], v[194:197], v[48:51]
	v_mfma_f32_16x16x32_bf16 v[104:107], v[178:181], v[202:205], v[104:107]
	v_mfma_f32_16x16x32_bf16 v[88:91], v[186:189], v[202:205], v[88:91]
	v_mfma_f32_16x16x32_bf16 v[96:99], v[178:181], v[210:213], v[96:99]
	v_mfma_f32_16x16x32_bf16 v[80:83], v[186:189], v[210:213], v[80:83]
	v_mfma_f32_16x16x32_bf16 v[36:39], v[178:181], v[218:221], v[36:39]
	v_mfma_f32_16x16x32_bf16 v[32:35], v[186:189], v[218:221], v[32:35]
	v_mfma_f32_16x16x32_bf16 v[52:55], v[182:185], v[198:201], v[52:55]
	v_mfma_f32_16x16x32_bf16 v[48:51], v[190:193], v[198:201], v[48:51]
	v_mfma_f32_16x16x32_bf16 v[104:107], v[182:185], v[206:209], v[104:107]
	v_mfma_f32_16x16x32_bf16 v[88:91], v[190:193], v[206:209], v[88:91]
	v_mfma_f32_16x16x32_bf16 v[96:99], v[182:185], v[214:217], v[96:99]
	v_mfma_f32_16x16x32_bf16 v[80:83], v[190:193], v[214:217], v[80:83]
	v_mfma_f32_16x16x32_bf16 v[36:39], v[182:185], v[222:225], v[36:39]
	v_mfma_f32_16x16x32_bf16 v[32:35], v[190:193], v[222:225], v[32:35]
	s_barrier
; #define PG8_STAGE(bufoff, gbase, voff) do { _Pragma("unroll") for (int _i = 0; _i < 2; ++_i) \
;         __builtin_amdgcn_global_load_lds((const unsigned*)((const char*)(gbase) + (voff)[_i]), (PG8_LAS unsigned*)(lds + (bufoff) + ldsw + _i * 8192), 16, 0, 0); } while (0)
; #define PG8_LDA(dst, b, h) do { _Pragma("unroll") for (int m = 0; m < 4; ++m) _Pragma("unroll") for (int k = 0; k < 2; ++k) dst[m][k] = *(const PG8_LAS bf16x8*)(lds + PG8_SA(b, h) + aoff + m * 2048 + k * 1024); } while (0)
; #define PG8_LDB(dst, b, h) do { _Pragma("unroll") for (int n = 0; n < 2; ++n) _Pragma("unroll") for (int k = 0; k < 2; ++k) dst[n][k] = *(const PG8_LAS bf16x8*)(lds + PG8_SB(b, h) + boff + n * 2048 + k * 1024); } while (0)
; #define PG8_MMA(ai, bj, At, Bt) do { __builtin_amdgcn_s_setprio(1); _Pragma("unroll") for (int m = 0; m < 4; ++m) _Pragma("unroll") for (int n = 0; n < 2; ++n) _Pragma("unroll") for (int k = 0; k < 2; ++k) \
;         acc[ai][bj][m][n] = __builtin_amdgcn_mfma_f32_16x16x32_bf16(Bt[n][k], At[m][k], acc[ai][bj][m][n], 0, 0, 0); __builtin_amdgcn_s_setprio(0); } while (0)
; #define PG8_WAIT_V(n) asm volatile("s_waitcnt vmcnt(" #n ")" ::: "memory")
; #define PG8_WAIT_L(n) asm volatile("s_waitcnt lgkmcnt(" #n ")" ::: "memory")
; #define PG8_BAR __builtin_amdgcn_s_barrier()
; #define PG8_SCHED __builtin_amdgcn_sched_barrier(0)
; template <class Epi, class Sched, bool ALIGN_EPI = false, bool SP2 = false>
; __device__ __forceinline__ void gemm_phase(PG8_LAS unsigned char* lds, const Gemm g, const Sched& S, const Epi& E) {
;     ...
;             PG8_LDB(B0, 1, 0); PG8_LDB(B1, 1, 1); PG8_SCHED; PG8_LDA(At, 1, 0); PG8_STAGE(PG8_SA(0, 1), a2 + hstepA, voffA);
;             PG8_WAIT_V(8); PG8_WAIT_L(0); PG8_BAR; PG8_MMA(0, 0, At, B0); PG8_MMA(0, 1, At, B1); PG8_BAR; PG8_SCHED;
;             PG8_LDA(At, 1, 1); PG8_STAGE(PG8_SB(1, 0), b3, voffB); PG8_STAGE(PG8_SB(1, 1), b3 + hstepB, voffB); PG8_STAGE(PG8_SA(1, 0), a3, voffA);
;             PG8_WAIT_V(8); PG8_WAIT_L(0); PG8_BAR; PG8_MMA(1, 0, At, B0); PG8_MMA(1, 1, At, B1); PG8_BAR; PG8_SCHED;
	s_add_i32 s14, s23, s2
	v_lshl_add_u64 v[226:227], v[226:227], 0, s[76:77]
	s_mov_b32 m0, s14
	ds_read_b128 v[194:197], v153 offset:49152
	ds_read_b128 v[198:201], v153 offset:50176
	ds_read_b128 v[202:205], v153 offset:51200
	ds_read_b128 v[206:209], v153 offset:52224
	ds_read_b128 v[210:213], v153 offset:53248
	ds_read_b128 v[214:217], v153 offset:54272
	ds_read_b128 v[218:221], v153 offset:55296
	ds_read_b128 v[222:225], v153 offset:56320
	global_load_lds_dwordx4 v[226:227], off
	s_add_i32 m0, s14, 0x2000
	s_add_u32 s12, s12, 0x80080
	v_lshl_add_u64 v[226:227], v[228:229], 0, s[76:77]
	s_addc_u32 s13, s13, 0
	s_add_i32 s14, s24, s2
	global_load_lds_dwordx4 v[226:227], off
	v_lshl_add_u64 v[226:227], s[12:13], 0, v[134:135]
	s_mov_b32 m0, s14
	s_nop 0
	global_load_lds_dwordx4 v[226:227], off
	v_lshl_add_u64 v[226:227], s[12:13], 0, v[130:131]
	s_add_i32 m0, s14, 0x2000
	s_nop 0
	global_load_lds_dwordx4 v[226:227], off
	v_lshl_add_u64 v[226:227], v[230:231], 0, s[76:77]
	s_mov_b32 m0, s74
	s_nop 0
	global_load_lds_dwordx4 v[226:227], off
	v_lshl_add_u64 v[226:227], v[232:233], 0, s[76:77]
	s_mov_b32 m0, s75
	s_nop 0
	global_load_lds_dwordx4 v[226:227], off
	s_waitcnt vmcnt(8)
	s_waitcnt lgkmcnt(0)
	s_barrier
	s_waitcnt lgkmcnt(0)
	v_mfma_f32_16x16x32_bf16 v[28:31], v[162:165], v[194:197], v[28:31]
	v_mfma_f32_16x16x32_bf16 v[24:27], v[170:173], v[194:197], v[24:27]
	v_mfma_f32_16x16x32_bf16 v[124:127], v[162:165], v[202:205], v[124:127]
	v_mfma_f32_16x16x32_bf16 v[76:79], v[170:173], v[202:205], v[76:79]
	v_mfma_f32_16x16x32_bf16 v[116:119], v[162:165], v[210:213], v[116:119]
	v_mfma_f32_16x16x32_bf16 v[68:71], v[170:173], v[210:213], v[68:71]
	v_mfma_f32_16x16x32_bf16 v[12:15], v[162:165], v[218:221], v[12:15]
	v_mfma_f32_16x16x32_bf16 v[8:11], v[170:173], v[218:221], v[8:11]
	v_mfma_f32_16x16x32_bf16 v[28:31], v[166:169], v[198:201], v[28:31]
	v_mfma_f32_16x16x32_bf16 v[24:27], v[174:177], v[198:201], v[24:27]
	v_mfma_f32_16x16x32_bf16 v[124:127], v[166:169], v[206:209], v[124:127]
	v_mfma_f32_16x16x32_bf16 v[76:79], v[174:177], v[206:209], v[76:79]
	v_mfma_f32_16x16x32_bf16 v[116:119], v[166:169], v[214:217], v[116:119]
	v_mfma_f32_16x16x32_bf16 v[68:71], v[174:177], v[214:217], v[68:71]
	v_mfma_f32_16x16x32_bf16 v[12:15], v[166:169], v[222:225], v[12:15]
	v_mfma_f32_16x16x32_bf16 v[8:11], v[174:177], v[222:225], v[8:11]
	v_mfma_f32_16x16x32_bf16 v[20:23], v[178:181], v[194:197], v[20:23]
	v_mfma_f32_16x16x32_bf16 v[16:19], v[186:189], v[194:197], v[16:19]
	v_mfma_f32_16x16x32_bf16 v[120:123], v[178:181], v[202:205], v[120:123]
	v_mfma_f32_16x16x32_bf16 v[72:75], v[186:189], v[202:205], v[72:75]
	v_mfma_f32_16x16x32_bf16 v[112:115], v[178:181], v[210:213], v[112:115]
	v_mfma_f32_16x16x32_bf16 v[64:67], v[186:189], v[210:213], v[64:67]
	v_mfma_f32_16x16x32_bf16 v[4:7], v[178:181], v[218:221], v[4:7]
	v_mfma_f32_16x16x32_bf16 v[0:3], v[186:189], v[218:221], v[0:3]
	v_mfma_f32_16x16x32_bf16 v[20:23], v[182:185], v[198:201], v[20:23]
	v_mfma_f32_16x16x32_bf16 v[16:19], v[190:193], v[198:201], v[16:19]
	v_mfma_f32_16x16x32_bf16 v[120:123], v[182:185], v[206:209], v[120:123]
	v_mfma_f32_16x16x32_bf16 v[72:75], v[190:193], v[206:209], v[72:75]
	v_mfma_f32_16x16x32_bf16 v[112:115], v[182:185], v[214:217], v[112:115]
	v_mfma_f32_16x16x32_bf16 v[64:67], v[190:193], v[214:217], v[64:67]
	v_mfma_f32_16x16x32_bf16 v[4:7], v[182:185], v[222:225], v[4:7]
	v_mfma_f32_16x16x32_bf16 v[0:3], v[190:193], v[222:225], v[0:3]
	s_barrier
	s_add_i32 s22, s22, 2
	s_add_u32 s8, s8, 0x100
	s_addc_u32 s9, s9, 0
	s_add_u32 s20, s20, 0x100
	s_addc_u32 s21, s21, 0
	s_cmp_gt_u32 s22, 29
	s_cbranch_scc0 .LBB0_2208
	v_readlane_b32 s8, v255, 55
	v_readlane_b32 s9, v255, 56
	s_and_b64 vcc, exec, s[8:9]
	s_cbranch_vccz .LBB0_2211
	s_barrier

; #define PG8_STAGE(bufoff, gbase, voff) do { _Pragma("unroll") for (int _i = 0; _i < 2; ++_i) \
;         __builtin_amdgcn_global_load_lds((const unsigned*)((const char*)(gbase) + (voff)[_i]), (PG8_LAS unsigned*)(lds + (bufoff) + ldsw + _i * 8192), 16, 0, 0); } while (0)
; #define PG8_LDA(dst, b, h) do { _Pragma("unroll") for (int m = 0; m < 4; ++m) _Pragma("unroll") for (int k = 0; k < 2; ++k) dst[m][k] = *(const PG8_LAS bf16x8*)(lds + PG8_SA(b, h) + aoff + m * 2048 + k * 1024); } while (0)
; #define PG8_LDB(dst, b, h) do { _Pragma("unroll") for (int n = 0; n < 2; ++n) _Pragma("unroll") for (int k = 0; k < 2; ++k) dst[n][k] = *(const PG8_LAS bf16x8*)(lds + PG8_SB(b, h) + boff + n * 2048 + k * 1024); } while (0)
; #define PG8_MMA(ai, bj, At, Bt) do { __builtin_amdgcn_s_setprio(1); _Pragma("unroll") for (int m = 0; m < 4; ++m) _Pragma("unroll") for (int n = 0; n < 2; ++n) _Pragma("unroll") for (int k = 0; k < 2; ++k) \
;         acc[ai][bj][m][n] = __builtin_amdgcn_mfma_f32_16x16x32_bf16(Bt[n][k], At[m][k], acc[ai][bj][m][n], 0, 0, 0); __builtin_amdgcn_s_setprio(0); } while (0)
; #define PG8_WAIT_V(n) asm volatile("s_waitcnt vmcnt(" #n ")" ::: "memory")
; #define PG8_WAIT_L(n) asm volatile("s_waitcnt lgkmcnt(" #n ")" ::: "memory")
; #define PG8_BAR __builtin_amdgcn_s_barrier()
; #define PG8_SCHED __builtin_amdgcn_sched_barrier(0)
; template <class Epi, class Sched, bool ALIGN_EPI = false, bool SP2 = false>
; __device__ __forceinline__ void gemm_phase(PG8_LAS unsigned char* lds, const Gemm g, const Sched& S, const Epi& E) {
;     ...
;             PG8_LDB(B0, 0, 0); PG8_LDB(B1, 0, 1); PG8_SCHED; PG8_LDA(At, 0, 0); PG8_STAGE(PG8_SA(1, 1), a1 + hstepA, voffA);
;             PG8_WAIT_V(8); PG8_WAIT_L(0); PG8_BAR; PG8_MMA(0, 0, At, B0); PG8_MMA(0, 1, At, B1); PG8_BAR; PG8_SCHED;
;             PG8_LDA(At, 0, 1); PG8_STAGE(PG8_SB(0, 0), b2, voffB); PG8_STAGE(PG8_SB(0, 1), b2 + hstepB, voffB); PG8_STAGE(PG8_SA(0, 0), a2, voffA);
;             PG8_WAIT_V(8); PG8_WAIT_L(0); PG8_BAR; PG8_MMA(1, 0, At, B0); PG8_MMA(1, 1, At, B1); PG8_BAR; PG8_SCHED;
;             PG8_LDB(B0, 1, 0); PG8_LDB(B1, 1, 1); PG8_SCHED; PG8_LDA(At, 1, 0); PG8_STAGE(PG8_SA(0, 1), a2 + hstepA, voffA);
.LBB0_2364:
	ds_read_b128 v[146:149], v157
	ds_read_b128 v[150:153], v157 offset:1024
	ds_read_b128 v[160:163], v157 offset:2048
	ds_read_b128 v[164:167], v157 offset:3072
	ds_read_b128 v[168:171], v158
	ds_read_b128 v[172:175], v158 offset:1024
	ds_read_b128 v[176:179], v158 offset:2048
	ds_read_b128 v[180:183], v158 offset:3072
	s_add_u32 s18, s4, 0xffea0080
	s_addc_u32 s19, s5, -1
	s_cmpk_eq_i32 s49, 0x54
	s_cselect_b32 s21, s15, s19
	s_cselect_b32 s20, s14, s18
	s_cselect_b32 s19, s17, s48
	s_cselect_b32 s18, s16, s47
	v_lshl_add_u64 v[216:217], s[4:5], 0, v[138:139]
	s_add_i32 m0, s27, 0xc000
	ds_read_b128 v[184:187], v159
	ds_read_b128 v[188:191], v159 offset:1024
	ds_read_b128 v[192:195], v159 offset:2048
	ds_read_b128 v[196:199], v159 offset:3072
	ds_read_b128 v[200:203], v159 offset:4096
	ds_read_b128 v[204:207], v159 offset:5120
	ds_read_b128 v[208:211], v159 offset:6144
	ds_read_b128 v[212:215], v159 offset:7168
	global_load_lds_dwordx4 v[216:217], off
	v_lshl_add_u64 v[216:217], s[4:5], 0, v[140:141]
	s_add_i32 m0, s27, 0xe000
	s_nop 0
	global_load_lds_dwordx4 v[216:217], off
	s_waitcnt vmcnt(8)
	s_waitcnt lgkmcnt(0)
	s_barrier
	s_waitcnt lgkmcnt(0)
	v_mfma_f32_16x16x32_bf16 v[124:127], v[146:149], v[184:187], v[124:127]
	v_mfma_f32_16x16x32_bf16 v[120:123], v[160:163], v[184:187], v[120:123]
	v_mfma_f32_16x16x32_bf16 v[108:111], v[146:149], v[192:195], v[108:111]
	v_mfma_f32_16x16x32_bf16 v[104:107], v[160:163], v[192:195], v[104:107]
	v_mfma_f32_16x16x32_bf16 v[92:95], v[146:149], v[200:203], v[92:95]
	v_mfma_f32_16x16x32_bf16 v[88:91], v[160:163], v[200:203], v[88:91]
	v_mfma_f32_16x16x32_bf16 v[76:79], v[146:149], v[208:211], v[76:79]
	v_mfma_f32_16x16x32_bf16 v[72:75], v[160:163], v[208:211], v[72:75]
	v_mfma_f32_16x16x32_bf16 v[124:127], v[150:153], v[188:191], v[124:127]
	v_mfma_f32_16x16x32_bf16 v[120:123], v[164:167], v[188:191], v[120:123]
	v_mfma_f32_16x16x32_bf16 v[108:111], v[150:153], v[196:199], v[108:111]
	v_mfma_f32_16x16x32_bf16 v[104:107], v[164:167], v[196:199], v[104:107]
	v_mfma_f32_16x16x32_bf16 v[92:95], v[150:153], v[204:207], v[92:95]
	v_mfma_f32_16x16x32_bf16 v[88:91], v[164:167], v[204:207], v[88:91]
	v_mfma_f32_16x16x32_bf16 v[76:79], v[150:153], v[212:215], v[76:79]
	v_mfma_f32_16x16x32_bf16 v[72:75], v[164:167], v[212:215], v[72:75]
	v_mfma_f32_16x16x32_bf16 v[116:119], v[168:171], v[184:187], v[116:119]
	v_mfma_f32_16x16x32_bf16 v[112:115], v[176:179], v[184:187], v[112:115]
	v_mfma_f32_16x16x32_bf16 v[100:103], v[168:171], v[192:195], v[100:103]
	v_mfma_f32_16x16x32_bf16 v[96:99], v[176:179], v[192:195], v[96:99]
	v_mfma_f32_16x16x32_bf16 v[84:87], v[168:171], v[200:203], v[84:87]
	v_mfma_f32_16x16x32_bf16 v[80:83], v[176:179], v[200:203], v[80:83]
	v_mfma_f32_16x16x32_bf16 v[68:71], v[168:171], v[208:211], v[68:71]
	v_mfma_f32_16x16x32_bf16 v[64:67], v[176:179], v[208:211], v[64:67]
	v_mfma_f32_16x16x32_bf16 v[116:119], v[172:175], v[188:191], v[116:119]
	v_mfma_f32_16x16x32_bf16 v[112:115], v[180:183], v[188:191], v[112:115]
	v_mfma_f32_16x16x32_bf16 v[100:103], v[172:175], v[196:199], v[100:103]
	v_mfma_f32_16x16x32_bf16 v[96:99], v[180:183], v[196:199], v[96:99]
	v_mfma_f32_16x16x32_bf16 v[84:87], v[172:175], v[204:207], v[84:87]
	v_mfma_f32_16x16x32_bf16 v[80:83], v[180:183], v[204:207], v[80:83]
	v_mfma_f32_16x16x32_bf16 v[68:71], v[172:175], v[212:215], v[68:71]
	v_mfma_f32_16x16x32_bf16 v[64:67], v[180:183], v[212:215], v[64:67]
	s_barrier
	s_add_i32 s50, s39, s26
	v_lshl_add_u64 v[216:217], s[18:19], 0, v[132:133]
	s_mov_b32 m0, s50
	ds_read_b128 v[184:187], v159 offset:16384
	ds_read_b128 v[188:191], v159 offset:17408
	ds_read_b128 v[192:195], v159 offset:18432
	ds_read_b128 v[196:199], v159 offset:19456
	ds_read_b128 v[200:203], v159 offset:20480
	ds_read_b128 v[204:207], v159 offset:21504
	ds_read_b128 v[208:211], v159 offset:22528
	ds_read_b128 v[212:215], v159 offset:23552
	global_load_lds_dwordx4 v[216:217], off
	s_add_i32 m0, s50, 0x2000
	s_add_u32 s50, s18, 0x160000
	v_lshl_add_u64 v[218:219], s[18:19], 0, v[136:137]
	s_addc_u32 s51, s19, 0
	s_add_i32 s52, s40, s26
	global_load_lds_dwordx4 v[218:219], off
	v_lshl_add_u64 v[220:221], s[50:51], 0, v[132:133]
	s_mov_b32 m0, s52
	v_lshl_add_u64 v[222:223], s[20:21], 0, v[134:135]
	global_load_lds_dwordx4 v[220:221], off
	v_lshl_add_u64 v[220:221], s[50:51], 0, v[136:137]
	s_add_i32 m0, s52, 0x2000
	s_nop 0
	global_load_lds_dwordx4 v[220:221], off
	v_lshl_add_u64 v[220:221], s[20:21], 0, v[130:131]
	s_mov_b32 m0, s27
	s_nop 0
	global_load_lds_dwordx4 v[220:221], off
	s_mov_b32 m0, s28
	s_nop 0
	global_load_lds_dwordx4 v[222:223], off
	s_waitcnt vmcnt(8)
	s_waitcnt lgkmcnt(0)
	s_barrier
; #define PG8_STAGE(bufoff, gbase, voff) do { _Pragma("unroll") for (int _i = 0; _i < 2; ++_i) \
;         __builtin_amdgcn_global_load_lds((const unsigned*)((const char*)(gbase) + (voff)[_i]), (PG8_LAS unsigned*)(lds + (bufoff) + ldsw + _i * 8192), 16, 0, 0); } while (0)
; #define PG8_LDA(dst, b, h) do { _Pragma("unroll") for (int m = 0; m < 4; ++m) _Pragma("unroll") for (int k = 0; k < 2; ++k) dst[m][k] = *(const PG8_LAS bf16x8*)(lds + PG8_SA(b, h) + aoff + m * 2048 + k * 1024); } while (0)
; #define PG8_LDB(dst, b, h) do { _Pragma("unroll") for (int n = 0; n < 2; ++n) _Pragma("unroll") for (int k = 0; k < 2; ++k) dst[n][k] = *(const PG8_LAS bf16x8*)(lds + PG8_SB(b, h) + boff + n * 2048 + k * 1024); } while (0)
; #define PG8_MMA(ai, bj, At, Bt) do { __builtin_amdgcn_s_setprio(1); _Pragma("unroll") for (int m = 0; m < 4; ++m) _Pragma("unroll") for (int n = 0; n < 2; ++n) _Pragma("unroll") for (int k = 0; k < 2; ++k) \
;         acc[ai][bj][m][n] = __builtin_amdgcn_mfma_f32_16x16x32_bf16(Bt[n][k], At[m][k], acc[ai][bj][m][n], 0, 0, 0); __builtin_amdgcn_s_setprio(0); } while (0)
; #define PG8_WAIT_V(n) asm volatile("s_waitcnt vmcnt(" #n ")" ::: "memory")
; #define PG8_WAIT_L(n) asm volatile("s_waitcnt lgkmcnt(" #n ")" ::: "memory")
; #define PG8_BAR __builtin_amdgcn_s_barrier()
; #define PG8_SCHED __builtin_amdgcn_sched_barrier(0)
; template <class Epi, class Sched, bool ALIGN_EPI = false, bool SP2 = false>
; __device__ __forceinline__ void gemm_phase(PG8_LAS unsigned char* lds, const Gemm g, const Sched& S, const Epi& E) {
;     ...
;             PG8_WAIT_V(8); PG8_WAIT_L(0); PG8_BAR; PG8_MMA(0, 0, At, B0); PG8_MMA(0, 1, At, B1); PG8_BAR; PG8_SCHED;
;             PG8_LDA(At, 0, 1); PG8_STAGE(PG8_SB(0, 0), b2, voffB); PG8_STAGE(PG8_SB(0, 1), b2 + hstepB, voffB); PG8_STAGE(PG8_SA(0, 0), a2, voffA);
;             PG8_WAIT_V(8); PG8_WAIT_L(0); PG8_BAR; PG8_MMA(1, 0, At, B0); PG8_MMA(1, 1, At, B1); PG8_BAR; PG8_SCHED;
;             PG8_LDB(B0, 1, 0); PG8_LDB(B1, 1, 1); PG8_SCHED; PG8_LDA(At, 1, 0); PG8_STAGE(PG8_SA(0, 1), a2 + hstepA, voffA);
;             PG8_WAIT_V(8); PG8_WAIT_L(0); PG8_BAR; PG8_MMA(0, 0, At, B0); PG8_MMA(0, 1, At, B1); PG8_BAR; PG8_SCHED;
;             PG8_LDA(At, 1, 1); PG8_STAGE(PG8_SB(1, 0), b3, voffB); PG8_STAGE(PG8_SB(1, 1), b3 + hstepB, voffB); PG8_STAGE(PG8_SA(1, 0), a3, voffA);
	s_waitcnt lgkmcnt(0)
	v_mfma_f32_16x16x32_bf16 v[60:63], v[146:149], v[184:187], v[60:63]
	v_mfma_f32_16x16x32_bf16 v[56:59], v[160:163], v[184:187], v[56:59]
	v_mfma_f32_16x16x32_bf16 v[44:47], v[146:149], v[192:195], v[44:47]
	v_mfma_f32_16x16x32_bf16 v[40:43], v[160:163], v[192:195], v[40:43]
	v_mfma_f32_16x16x32_bf16 v[28:31], v[146:149], v[200:203], v[28:31]
	v_mfma_f32_16x16x32_bf16 v[24:27], v[160:163], v[200:203], v[24:27]
	v_mfma_f32_16x16x32_bf16 v[12:15], v[146:149], v[208:211], v[12:15]
	v_mfma_f32_16x16x32_bf16 v[8:11], v[160:163], v[208:211], v[8:11]
	v_mfma_f32_16x16x32_bf16 v[60:63], v[150:153], v[188:191], v[60:63]
	v_mfma_f32_16x16x32_bf16 v[56:59], v[164:167], v[188:191], v[56:59]
	v_mfma_f32_16x16x32_bf16 v[44:47], v[150:153], v[196:199], v[44:47]
	v_mfma_f32_16x16x32_bf16 v[40:43], v[164:167], v[196:199], v[40:43]
	v_mfma_f32_16x16x32_bf16 v[28:31], v[150:153], v[204:207], v[28:31]
	v_mfma_f32_16x16x32_bf16 v[24:27], v[164:167], v[204:207], v[24:27]
	v_mfma_f32_16x16x32_bf16 v[12:15], v[150:153], v[212:215], v[12:15]
	v_mfma_f32_16x16x32_bf16 v[8:11], v[164:167], v[212:215], v[8:11]
	v_mfma_f32_16x16x32_bf16 v[52:55], v[168:171], v[184:187], v[52:55]
	v_mfma_f32_16x16x32_bf16 v[48:51], v[176:179], v[184:187], v[48:51]
	v_mfma_f32_16x16x32_bf16 v[36:39], v[168:171], v[192:195], v[36:39]
	v_mfma_f32_16x16x32_bf16 v[32:35], v[176:179], v[192:195], v[32:35]
	v_mfma_f32_16x16x32_bf16 v[20:23], v[168:171], v[200:203], v[20:23]
	v_mfma_f32_16x16x32_bf16 v[16:19], v[176:179], v[200:203], v[16:19]
	v_mfma_f32_16x16x32_bf16 v[4:7], v[168:171], v[208:211], v[4:7]
	v_mfma_f32_16x16x32_bf16 v[0:3], v[176:179], v[208:211], v[0:3]
	v_mfma_f32_16x16x32_bf16 v[52:55], v[172:175], v[188:191], v[52:55]
	v_mfma_f32_16x16x32_bf16 v[48:51], v[180:183], v[188:191], v[48:51]
	v_mfma_f32_16x16x32_bf16 v[36:39], v[172:175], v[196:199], v[36:39]
	v_mfma_f32_16x16x32_bf16 v[32:35], v[180:183], v[196:199], v[32:35]
	v_mfma_f32_16x16x32_bf16 v[20:23], v[172:175], v[204:207], v[20:23]
	v_mfma_f32_16x16x32_bf16 v[16:19], v[180:183], v[204:207], v[16:19]
	v_mfma_f32_16x16x32_bf16 v[4:7], v[172:175], v[212:215], v[4:7]
	v_mfma_f32_16x16x32_bf16 v[0:3], v[180:183], v[212:215], v[0:3]
	s_barrier
	s_add_i32 s50, 0, 0x18000
	v_add_u32_e32 v128, s50, v155
	s_add_i32 s51, 0, 0x1c000
	ds_read_b128 v[146:149], v128
	ds_read_b128 v[150:153], v128 offset:1024
	ds_read_b128 v[160:163], v128 offset:2048
	ds_read_b128 v[164:167], v128 offset:3072
	v_add_u32_e32 v128, s51, v155
	ds_read_b128 v[168:171], v128
	ds_read_b128 v[172:175], v128 offset:1024
	ds_read_b128 v[176:179], v128 offset:2048
	ds_read_b128 v[180:183], v128 offset:3072
	s_add_u32 s20, s20, 0x160000
	s_addc_u32 s21, s21, 0
	s_mov_b32 m0, s29
	v_lshl_add_u64 v[224:225], s[20:21], 0, v[130:131]
	ds_read_b128 v[184:187], v159 offset:32768
	ds_read_b128 v[188:191], v159 offset:33792
	ds_read_b128 v[192:195], v159 offset:34816
	ds_read_b128 v[196:199], v159 offset:35840
	ds_read_b128 v[200:203], v159 offset:36864
	ds_read_b128 v[204:207], v159 offset:37888
	ds_read_b128 v[208:211], v159 offset:38912
	ds_read_b128 v[212:215], v159 offset:39936
	global_load_lds_dwordx4 v[224:225], off
	v_lshl_add_u64 v[224:225], s[20:21], 0, v[134:135]
	s_mov_b32 m0, s30
	s_nop 0
	global_load_lds_dwordx4 v[224:225], off
	s_waitcnt vmcnt(8)
	s_waitcnt lgkmcnt(0)
	s_barrier
	s_waitcnt lgkmcnt(0)
	v_mfma_f32_16x16x32_bf16 v[124:127], v[146:149], v[184:187], v[124:127]
	v_mfma_f32_16x16x32_bf16 v[120:123], v[160:163], v[184:187], v[120:123]
	v_mfma_f32_16x16x32_bf16 v[108:111], v[146:149], v[192:195], v[108:111]
	v_mfma_f32_16x16x32_bf16 v[104:107], v[160:163], v[192:195], v[104:107]
	v_mfma_f32_16x16x32_bf16 v[92:95], v[146:149], v[200:203], v[92:95]
	v_mfma_f32_16x16x32_bf16 v[88:91], v[160:163], v[200:203], v[88:91]
	v_mfma_f32_16x16x32_bf16 v[76:79], v[146:149], v[208:211], v[76:79]
	v_mfma_f32_16x16x32_bf16 v[72:75], v[160:163], v[208:211], v[72:75]
	v_mfma_f32_16x16x32_bf16 v[124:127], v[150:153], v[188:191], v[124:127]
	v_mfma_f32_16x16x32_bf16 v[120:123], v[164:167], v[188:191], v[120:123]
	v_mfma_f32_16x16x32_bf16 v[108:111], v[150:153], v[196:199], v[108:111]
	v_mfma_f32_16x16x32_bf16 v[104:107], v[164:167], v[196:199], v[104:107]
	v_mfma_f32_16x16x32_bf16 v[92:95], v[150:153], v[204:207], v[92:95]
	v_mfma_f32_16x16x32_bf16 v[88:91], v[164:167], v[204:207], v[88:91]
	v_mfma_f32_16x16x32_bf16 v[76:79], v[150:153], v[212:215], v[76:79]
	v_mfma_f32_16x16x32_bf16 v[72:75], v[164:167], v[212:215], v[72:75]
	v_mfma_f32_16x16x32_bf16 v[116:119], v[168:171], v[184:187], v[116:119]
	v_mfma_f32_16x16x32_bf16 v[112:115], v[176:179], v[184:187], v[112:115]
	v_mfma_f32_16x16x32_bf16 v[100:103], v[168:171], v[192:195], v[100:103]
	v_mfma_f32_16x16x32_bf16 v[96:99], v[176:179], v[192:195], v[96:99]
	v_mfma_f32_16x16x32_bf16 v[84:87], v[168:171], v[200:203], v[84:87]
	v_mfma_f32_16x16x32_bf16 v[80:83], v[176:179], v[200:203], v[80:83]
	v_mfma_f32_16x16x32_bf16 v[68:71], v[168:171], v[208:211], v[68:71]
	v_mfma_f32_16x16x32_bf16 v[64:67], v[176:179], v[208:211], v[64:67]
	v_mfma_f32_16x16x32_bf16 v[116:119], v[172:175], v[188:191], v[116:119]
	v_mfma_f32_16x16x32_bf16 v[112:115], v[180:183], v[188:191], v[112:115]
	v_mfma_f32_16x16x32_bf16 v[100:103], v[172:175], v[196:199], v[100:103]
	v_mfma_f32_16x16x32_bf16 v[96:99], v[180:183], v[196:199], v[96:99]
	v_mfma_f32_16x16x32_bf16 v[84:87], v[172:175], v[204:207], v[84:87]
	v_mfma_f32_16x16x32_bf16 v[80:83], v[180:183], v[204:207], v[80:83]
	v_mfma_f32_16x16x32_bf16 v[68:71], v[172:175], v[212:215], v[68:71]
	v_mfma_f32_16x16x32_bf16 v[64:67], v[180:183], v[212:215], v[64:67]
	s_barrier
; #define PG8_STAGE(bufoff, gbase, voff) do { _Pragma("unroll") for (int _i = 0; _i < 2; ++_i) \
;         __builtin_amdgcn_global_load_lds((const unsigned*)((const char*)(gbase) + (voff)[_i]), (PG8_LAS unsigned*)(lds + (bufoff) + ldsw + _i * 8192), 16, 0, 0); } while (0)
; #define PG8_LDA(dst, b, h) do { _Pragma("unroll") for (int m = 0; m < 4; ++m) _Pragma("unroll") for (int k = 0; k < 2; ++k) dst[m][k] = *(const PG8_LAS bf16x8*)(lds + PG8_SA(b, h) + aoff + m * 2048 + k * 1024); } while (0)
; #define PG8_LDB(dst, b, h) do { _Pragma("unroll") for (int n = 0; n < 2; ++n) _Pragma("unroll") for (int k = 0; k < 2; ++k) dst[n][k] = *(const PG8_LAS bf16x8*)(lds + PG8_SB(b, h) + boff + n * 2048 + k * 1024); } while (0)
; #define PG8_MMA(ai, bj, At, Bt) do { __builtin_amdgcn_s_setprio(1); _Pragma("unroll") for (int m = 0; m < 4; ++m) _Pragma("unroll") for (int n = 0; n < 2; ++n) _Pragma("unroll") for (int k = 0; k < 2; ++k) \
;         acc[ai][bj][m][n] = __builtin_amdgcn_mfma_f32_16x16x32_bf16(Bt[n][k], At[m][k], acc[ai][bj][m][n], 0, 0, 0); __builtin_amdgcn_s_setprio(0); } while (0)
; #define PG8_WAIT_V(n) asm volatile("s_waitcnt vmcnt(" #n ")" ::: "memory")
; #define PG8_WAIT_L(n) asm volatile("s_waitcnt lgkmcnt(" #n ")" ::: "memory")
; #define PG8_BAR __builtin_amdgcn_s_barrier()
; #define PG8_SCHED __builtin_amdgcn_sched_barrier(0)
; template <class Epi, class Sched, bool ALIGN_EPI = false, bool SP2 = false>
; __device__ __forceinline__ void gemm_phase(PG8_LAS unsigned char* lds, const Gemm g, const Sched& S, const Epi& E) {
;     ...
;             PG8_LDB(B0, 1, 0); PG8_LDB(B1, 1, 1); PG8_SCHED; PG8_LDA(At, 1, 0); PG8_STAGE(PG8_SA(0, 1), a2 + hstepA, voffA);
;             PG8_WAIT_V(8); PG8_WAIT_L(0); PG8_BAR; PG8_MMA(0, 0, At, B0); PG8_MMA(0, 1, At, B1); PG8_BAR; PG8_SCHED;
;             PG8_LDA(At, 1, 1); PG8_STAGE(PG8_SB(1, 0), b3, voffB); PG8_STAGE(PG8_SB(1, 1), b3 + hstepB, voffB); PG8_STAGE(PG8_SA(1, 0), a3, voffA);
;             PG8_WAIT_V(8); PG8_WAIT_L(0); PG8_BAR; PG8_MMA(1, 0, At, B0); PG8_MMA(1, 1, At, B1); PG8_BAR; PG8_SCHED;
	s_add_i32 s20, s50, s26
	v_lshl_add_u64 v[216:217], v[216:217], 0, s[10:11]
	s_mov_b32 m0, s20
	ds_read_b128 v[184:187], v159 offset:49152
	ds_read_b128 v[188:191], v159 offset:50176
	ds_read_b128 v[192:195], v159 offset:51200
	ds_read_b128 v[196:199], v159 offset:52224
	ds_read_b128 v[200:203], v159 offset:53248
	ds_read_b128 v[204:207], v159 offset:54272
	ds_read_b128 v[208:211], v159 offset:55296
	ds_read_b128 v[212:215], v159 offset:56320
	global_load_lds_dwordx4 v[216:217], off
	s_add_i32 m0, s20, 0x2000
	s_add_u32 s18, s18, 0x160080
	v_lshl_add_u64 v[216:217], v[218:219], 0, s[10:11]
	s_addc_u32 s19, s19, 0
	s_add_i32 s20, s51, s26
	global_load_lds_dwordx4 v[216:217], off
	v_lshl_add_u64 v[216:217], s[18:19], 0, v[132:133]
	s_mov_b32 m0, s20
	s_nop 0
	global_load_lds_dwordx4 v[216:217], off
	v_lshl_add_u64 v[216:217], s[18:19], 0, v[136:137]
	s_add_i32 m0, s20, 0x2000
	s_nop 0
	global_load_lds_dwordx4 v[216:217], off
	v_lshl_add_u64 v[216:217], v[220:221], 0, s[10:11]
	s_mov_b32 m0, s34
	s_nop 0
	global_load_lds_dwordx4 v[216:217], off
	v_lshl_add_u64 v[216:217], v[222:223], 0, s[10:11]
	s_mov_b32 m0, s35
	s_nop 0
	global_load_lds_dwordx4 v[216:217], off
	s_waitcnt vmcnt(8)
	s_waitcnt lgkmcnt(0)
	s_barrier
	s_waitcnt lgkmcnt(0)
	v_mfma_f32_16x16x32_bf16 v[60:63], v[146:149], v[184:187], v[60:63]
	v_mfma_f32_16x16x32_bf16 v[56:59], v[160:163], v[184:187], v[56:59]
	v_mfma_f32_16x16x32_bf16 v[44:47], v[146:149], v[192:195], v[44:47]
	v_mfma_f32_16x16x32_bf16 v[40:43], v[160:163], v[192:195], v[40:43]
	v_mfma_f32_16x16x32_bf16 v[28:31], v[146:149], v[200:203], v[28:31]
	v_mfma_f32_16x16x32_bf16 v[24:27], v[160:163], v[200:203], v[24:27]
	v_mfma_f32_16x16x32_bf16 v[12:15], v[146:149], v[208:211], v[12:15]
	v_mfma_f32_16x16x32_bf16 v[8:11], v[160:163], v[208:211], v[8:11]
	v_mfma_f32_16x16x32_bf16 v[60:63], v[150:153], v[188:191], v[60:63]
	v_mfma_f32_16x16x32_bf16 v[56:59], v[164:167], v[188:191], v[56:59]
	v_mfma_f32_16x16x32_bf16 v[44:47], v[150:153], v[196:199], v[44:47]
	v_mfma_f32_16x16x32_bf16 v[40:43], v[164:167], v[196:199], v[40:43]
	v_mfma_f32_16x16x32_bf16 v[28:31], v[150:153], v[204:207], v[28:31]
	v_mfma_f32_16x16x32_bf16 v[24:27], v[164:167], v[204:207], v[24:27]
	v_mfma_f32_16x16x32_bf16 v[12:15], v[150:153], v[212:215], v[12:15]
	v_mfma_f32_16x16x32_bf16 v[8:11], v[164:167], v[212:215], v[8:11]
	v_mfma_f32_16x16x32_bf16 v[52:55], v[168:171], v[184:187], v[52:55]
	v_mfma_f32_16x16x32_bf16 v[48:51], v[176:179], v[184:187], v[48:51]
	v_mfma_f32_16x16x32_bf16 v[36:39], v[168:171], v[192:195], v[36:39]
	v_mfma_f32_16x16x32_bf16 v[32:35], v[176:179], v[192:195], v[32:35]
	v_mfma_f32_16x16x32_bf16 v[20:23], v[168:171], v[200:203], v[20:23]
	v_mfma_f32_16x16x32_bf16 v[16:19], v[176:179], v[200:203], v[16:19]
	v_mfma_f32_16x16x32_bf16 v[4:7], v[168:171], v[208:211], v[4:7]
	v_mfma_f32_16x16x32_bf16 v[0:3], v[176:179], v[208:211], v[0:3]
	v_mfma_f32_16x16x32_bf16 v[52:55], v[172:175], v[188:191], v[52:55]
	v_mfma_f32_16x16x32_bf16 v[48:51], v[180:183], v[188:191], v[48:51]
	v_mfma_f32_16x16x32_bf16 v[36:39], v[172:175], v[196:199], v[36:39]
	v_mfma_f32_16x16x32_bf16 v[32:35], v[180:183], v[196:199], v[32:35]
	v_mfma_f32_16x16x32_bf16 v[20:23], v[172:175], v[204:207], v[20:23]
	v_mfma_f32_16x16x32_bf16 v[16:19], v[180:183], v[204:207], v[16:19]
	v_mfma_f32_16x16x32_bf16 v[4:7], v[172:175], v[212:215], v[4:7]
	v_mfma_f32_16x16x32_bf16 v[0:3], v[180:183], v[212:215], v[0:3]
	s_barrier
	s_add_i32 s49, s49, 2
	s_add_u32 s4, s4, 0x100
	s_addc_u32 s5, s5, 0
	s_add_u32 s47, s47, 0x100
	s_addc_u32 s48, s48, 0
	s_cmpk_gt_u32 s49, 0x55
	s_cbranch_scc0 .LBB0_2364
	s_and_b64 vcc, exec, s[12:13]
	s_cbranch_vccz .LBB0_2367
	s_barrier

_ZL7IDX_TAB:
	.short	401
	.short	79
	.short	65535
	.short	416
	.short	64
	.short	65535
	.short	395
	.short	89
	.short	65535
	.short	393
	.short	87
	.short	65535
	.short	399
	.short	84
	.short	65535
	.short	390
	.short	88
	.short	65535
	.short	391
	.short	91
	.short	65535
	.short	410
	.short	66
	.short	65535
	.short	406
	.short	73
	.short	65535
	.short	384
	.short	98
	.short	65535
	.short	385
	.short	90
	.short	65535
	.short	377
	.short	104
	.short	65535
	.short	388
	.short	94
	.short	65535
	.short	378
	.short	105
	.short	65535
	.short	371
	.short	103
	.short	65535
	.short	381
	.short	92
	.short	65535
	.short	369
	.short	112
	.short	65535
	.short	370
	.short	99
	.short	65535
	.short	374
	.short	93
	.short	65535
	.short	364
	.short	109
	.short	65535
	.short	373
	.short	97
	.short	65535
	.short	362
	.short	107
	.short	65535
	.short	368
	.short	110
	.short	65535
	.short	354
	.short	119
	.short	65535
	.short	359
	.short	116
	.short	65535
	.short	363
	.short	111
	.short	65535
	.short	356
	.short	143
	.short	65535
	.short	351
	.short	140
	.short	65535
	.short	365
	.short	117
	.short	65535
	.short	360
	.short	123
	.short	65535
	.short	355
	.short	115
	.short	65535
	.short	353
	.short	131
	.short	65535
	.short	350
	.short	128
	.short	65535
	.short	352
	.short	150
	.short	65535
	.short	348
	.short	129
	.short	65535
	.short	347
	.short	124
	.short	65535
	.short	346
	.short	159
	.short	65535
	.short	349
	.short	122
	.short	65535
	.short	344
	.short	161
	.short	65535
	.short	345
	.short	137
	.short	65535
	.short	341
	.short	134
	.short	65535
	.short	343
	.short	163
	.short	65535
	.short	340
	.short	142
	.short	65535
	.short	342
	.short	130
	.short	65535
	.short	338
	.short	144
	.short	65535
	.short	339
	.short	146
	.short	65535
	.short	336
	.short	151
	.short	65535
	.short	337
	.short	141
	.short	65535
	.short	334
	.short	153
	.short	65535
	.short	335
	.short	174
	.short	65535
	.short	332
	.short	176
	.short	65535
	.short	333
	.short	177
	.short	65535
	.short	329
	.short	180
	.short	65535
	.short	331
	.short	179
	.short	65535
	.short	328
	.short	154
	.short	65535
	.short	330
	.short	178
	.short	65535
	.short	326
	.short	160
	.short	65535
	.short	327
	.short	165
	.short	65535
	.short	324
	.short	167
	.short	65535
	.short	325
	.short	183
	.short	65535
	.short	322
	.short	169
	.short	65535
	.short	323
	.short	181
	.short	65535
	.short	320
	.short	190
	.short	65535
	.short	321
	.short	191
	.short	65535
	.short	318
	.short	192
	.short	65535
	.short	319
	.short	193
	.short	65535
	.short	316
	.short	194
	.short	65535
	.short	317
	.short	195
	.short	65535
	.short	314
	.short	196
	.short	65535
	.short	315
	.short	197
	.short	65535
	.short	312
	.short	198
	.short	65535
	.short	313
	.short	199
	.short	65535
	.short	310
	.short	200
	.short	65535
	.short	311
	.short	201
	.short	65535
	.short	308
	.short	202
	.short	65535
	.short	309
	.short	203
	.short	65535
	.short	306
	.short	204
	.short	65535
	.short	307
	.short	205
	.short	65535
	.short	304
	.short	206
	.short	65535
	.short	305
	.short	207
	.short	65535
	.short	302
	.short	208
	.short	65535
	.short	303
	.short	209
	.short	65535
	.short	300
	.short	210
	.short	65535
	.short	301
	.short	211
	.short	65535
	.short	298
	.short	212
	.short	65535
	.short	299
	.short	213
	.short	65535
	.short	296
	.short	214
	.short	65535
	.short	297
	.short	215
	.short	65535
	.short	294
	.short	216
	.short	65535
	.short	295
	.short	217
	.short	65535
	.short	292
	.short	218
	.short	65535
	.short	293
	.short	219
	.short	65535
	.short	290
	.short	220
	.short	65535
	.short	291
	.short	221
	.short	65535
	.short	288
	.short	222
	.short	65535
	.short	289
	.short	223
	.short	65535
	.short	286
	.short	224
	.short	65535
	.short	287
	.short	225
	.short	65535
	.short	284
	.short	226
	.short	65535
	.short	285
	.short	227
	.short	65535
	.short	282
	.short	228
	.short	65535
	.short	283
	.short	229
	.short	65535
	.short	280
	.short	230
	.short	65535
	.short	281
	.short	231
	.short	65535
	.short	278
	.short	232
	.short	65535
	.short	279
	.short	233
	.short	65535
	.short	276
	.short	234
	.short	65535
	.short	277
	.short	235
	.short	65535
	.short	274
	.short	236
	.short	65535
	.short	275
	.short	237
	.short	65535
	.short	272
	.short	238
	.short	65535
	.short	273
	.short	239
	.short	65535
	.short	270
	.short	240
	.short	65535
	.short	271
	.short	241
	.short	65535
	.short	268
	.short	242
	.short	65535
	.short	269
	.short	243
	.short	65535
	.short	266
	.short	244
	.short	65535
	.short	267
	.short	245
	.short	65535
	.short	264
	.short	246
	.short	65535
	.short	265
	.short	247
	.short	65535
	.short	262
	.short	248
	.short	65535
	.short	263
	.short	249
	.short	65535
	.short	260
	.short	250
	.short	65535
	.short	261
	.short	251
	.short	65535
	.short	258
	.short	252
	.short	65535
	.short	259
	.short	253
	.short	65535
	.short	256
	.short	254
; __device__ __forceinline__ void idx_phase(const Args& a, unsigned char* lds, int tid, int lane, int wave) {
;     ...
;     for (int kk = 0; ; ++kk) {
;         int id;
;         if (use_tab) { if (kk >= IDX_TAB_N) break; id = IDX_TAB[blockIdx.x][kk]; if (id == 0xFFFF) break; }
;         else { const int it = blockIdx.x + kk * gridDim.x; if (it >= 528) break;
;                id = it < 256 ? (255 - (it >> 1)) * 2 + (it & 1) : (it < 512 ? ((it - 256) >> 1) * 2 + (it & 1) : it); }
;         int c, half = id & 1, bb = 0; bool sample = false;
;         if (id < 512) c = id >> 1;
;         else { sample = true; bb = (id - 512) >> 1; c = 256 + bb; }
;         const int L = sample ? 1088 : 64 * (c + 1), ntile = L >> 6;
	.short	65535
	.short	257
	.short	255
	.short	65535
	.short	508
	.short	16
	.short	65535
	.short	511
	.short	10
	.short	65535
	.short	510
	.short	12
	.short	65535
	.short	509
	.short	15
	.short	65535
	.short	506
	.short	20
	.short	65535
	.short	507
	.short	19
	.short	65535
	.short	504
	.short	22
	.short	65535
	.short	500
	.short	24
	.short	65535
	.short	502
	.short	23
	.short	65535
	.short	503
	.short	25
	.short	65535
	.short	505
	.short	21
	.short	65535
	.short	501
	.short	27
	.short	65535
	.short	498
	.short	18
	.short	65535
	.short	499
	.short	29
	.short	65535
	.short	496
	.short	30
	.short	65535
	.short	497
	.short	28
	.short	65535
	.short	491
	.short	526
	.short	65535
	.short	495
	.short	527
	.short	65535
	.short	492
	.short	524
	.short	65535
	.short	493
	.short	525
	.short	65535
	.short	490
	.short	522
	.short	65535
	.short	494
	.short	31
	.short	65535
	.short	488
	.short	520
	.short	65535
	.short	483
	.short	513
	.short	65535
	.short	486
	.short	518
	.short	65535
	.short	482
	.short	37
	.short	65535
	.short	484
	.short	516
	.short	65535
	.short	489
	.short	517
	.short	65535
	.short	487
	.short	514
	.short	65535
	.short	485
	.short	515
	.short	65535
	.short	480
	.short	38
	.short	65535
	.short	481
	.short	36
	.short	65535
	.short	478
	.short	32
	.short	9
	.short	479
	.short	35
	.short	3
	.short	472
	.short	521
	.short	17
	.short	463
	.short	519
	.short	26
	.short	474
	.short	523
	.short	11
	.short	476
	.short	512
	.short	13
	.short	475
	.short	33
	.short	8
	.short	439
	.short	42
	.short	34
	.short	470
	.short	40
	.short	6
	.short	471
	.short	39
	.short	7
	.short	467
	.short	45
	.short	4
	.short	469
	.short	43
	.short	5
	.short	466
	.short	47
	.short	2
	.short	458
	.short	46
	.short	14
	.short	464
	.short	51
	.short	0
	.short	465
	.short	49
	.short	1
	.short	468
	.short	48
	.short	65535
	.short	477
	.short	41
	.short	65535
	.short	460
	.short	50
	.short	65535
	.short	473
	.short	44
	.short	65535
	.short	462
	.short	52
	.short	65535
	.short	461
	.short	53
	.short	65535
	.short	456
	.short	57
	.short	65535
	.short	457
	.short	55
	.short	65535
	.short	454
	.short	56
	.short	65535
	.short	455
	.short	59
	.short	65535
	.short	452
	.short	58
	.short	65535
	.short	459
	.short	54
	.short	65535
	.short	453
	.short	60
	.short	65535
	.short	451
	.short	61
	.short	65535
	.short	448
	.short	62
	.short	65535
	.short	450
	.short	63
	.short	65535
	.short	449
	.short	72
	.short	65535
	.short	447
	.short	65
	.short	65535
	.short	444
	.short	75
	.short	65535
	.short	446
	.short	67
	.short	65535
	.short	442
	.short	68
	.short	65535
	.short	445
	.short	69
	.short	65535
	.short	443
	.short	70
	.short	65535
	.short	441
	.short	71
	.short	65535
	.short	438
	.short	76
	.short	65535
	.short	440
	.short	80
	.short	65535
	.short	436
	.short	74
	.short	65535
	.short	437
	.short	77
	.short	65535
	.short	434
	.short	86
	.short	65535
	.short	430
	.short	95
	.short	65535
	.short	435
	.short	78
	.short	65535
	.short	433
	.short	81
	.short	65535
	.short	432
	.short	82
	.short	65535
	.short	431
	.short	83
	.short	65535
	.short	428
	.short	85
	.short	65535
	.short	426
	.short	101
	.short	65535
	.short	429
	.short	96
	.short	65535
	.short	427
	.short	100
	.short	65535
	.short	424
	.short	102
	.short	65535
	.short	422
	.short	114
	.short	65535
	.short	425
	.short	108
	.short	65535
	.short	423
	.short	120
	.short	65535
	.short	418
	.short	113
	.short	65535
	.short	421
	.short	125
	.short	65535
	.short	420
	.short	106
	.short	65535
	.short	419
	.short	126
	.short	65535
	.short	413
	.short	121
	.short	65535
	.short	417
	.short	127
	.short	65535
	.short	407
	.short	149
	.short	65535
	.short	408
	.short	132
	.short	65535
	.short	414
	.short	136
	.short	65535
	.short	415
	.short	118
	.short	65535
	.short	403
	.short	148
	.short	65535
	.short	412
	.short	135
	.short	65535
	.short	411
	.short	133
	.short	65535
	.short	400
	.short	147
	.short	65535
	.short	404
	.short	145
	.short	65535
	.short	409
	.short	138
	.short	65535
	.short	398
	.short	158
	.short	65535
	.short	405
	.short	139
	.short	65535
	.short	402
	.short	157
	.short	65535
	.short	396
	.short	152
	.short	65535
	.short	392
	.short	164
	.short	65535
	.short	394
	.short	155
	.short	65535
	.short	383
	.short	168
	.short	65535
	.short	389
	.short	166
	.short	65535
	.short	387
	.short	162
	.short	65535
	.short	397
	.short	156
	.short	65535
	.short	386
	.short	173
	.short	65535
	.short	376
	.short	172
	.short	65535
	.short	375
	.short	182
	.short	65535
	.short	372
	.short	184
	.short	65535
	.short	380
	.short	170
	.short	65535
	.short	379
	.short	175
	.short	65535
	.short	382
	.short	171
	.short	65535
	.short	366
	.short	185
	.short	65535
	.short	357
	.short	189
	.short	65535
	.short	358
	.short	187
	.short	65535
	.short	361
	.short	188
	.short	65535
	.short	367
	.short	186
	.short	65535
	.size	_ZL7IDX_TAB, 1536

	.type	__hip_cuid_61d45634659d28aa,@object
